# GEMM mainloops (in-proj, wout, pq, branch): B-side LDS fragments buffered through idle registers so reads run ahead of the MFMAs
# speedup vs baseline: 1.0287x; 1.0076x over previous
; __device__ __forceinline__ f32x4 mfma16(bf16x8 a, bf16x8 b, f32x4 c) { return __builtin_amdgcn_mfma_f32_16x16x32_bf16(a, b, c, 0, 0, 0); }
; __device__ __forceinline__ void lds_barrier() { asm volatile("s_waitcnt lgkmcnt(0)\n\ts_barrier" ::: "memory"); }
; template <bool PF2>
; __device__ __forceinline__ void gemm_mainloop_t(const bf16_t* __restrict__ A, int lda, const bf16_t* __restrict__ Bt, int ldb, int K,
;                                                 bf16_t* smem, f32x4 (&acc)[4][4], const int tid) {
;     ...
;   auto compute = [&](int st) {
;     const bf16_t* as = smem + st * 2 * GSTAGE;
;     const bf16_t* bs = as + GSTAGE;
; #pragma unroll
;     for (int ks = 0; ks < 2; ++ks) {
;       bf16x8 af[4], bfr[4];
; #pragma unroll
;       for (int mi = 0; mi < 4; ++mi) af[mi] = *(const bf16x8*)(as + (wm * 64 + mi * 16 + fr) * GS + (((ks * 4 + fq) ^ (fr & 7)) * 8));
; #pragma unroll
;       for (int ni = 0; ni < 4; ++ni) bfr[ni] = *(const bf16x8*)(bs + (wn * 64 + ni * 16 + fr) * GS + (((ks * 4 + fq) ^ (fr & 7)) * 8));
; #pragma unroll
;       for (int mi = 0; mi < 4; ++mi)
; #pragma unroll
;         for (int ni = 0; ni < 4; ++ni) acc[mi][ni] = mfma16(bfr[ni], af[mi], acc[mi][ni]);
;     }
;   };
;     ...
;     for (int kt = 0; kt < nk; kt += 2) {
;       gload(0, min(kt + 2, nk - 1));
;       __builtin_amdgcn_sched_barrier(0);
;       compute(0);
;       sstore(1, 1);
;       lds_barrier();
;       gload(1, min(kt + 3, nk - 1));
;       __builtin_amdgcn_sched_barrier(0);
;       compute(1);
;       sstore(0, 0);
;       lds_barrier();
;     }
.Lrot178_body:
	ds_read_b128 v[168:171], v162 offset:16384
	ds_read_b128 v[176:179], v161
	ds_read_b128 v[172:175], v162 offset:18432
	ds_read_b128 v[184:187], v162 offset:20480
	ds_read_b128 v[202:205], v162 offset:22528
	ds_read_b128 v[180:183], v161 offset:2048
	ds_read_b128 v[206:209], v161 offset:4096
	s_min_u32 s1, s0, 12
	s_waitcnt lgkmcnt(5)
	v_mfma_f32_16x16x32_bf16 v[90:93], v[168:171], v[176:179], v[90:93]
	s_lshl_b32 s74, s1, 7
	s_waitcnt lgkmcnt(4)
	v_mfma_f32_16x16x32_bf16 v[86:89], v[172:175], v[176:179], v[86:89]
	s_waitcnt lgkmcnt(3)
	v_mfma_f32_16x16x32_bf16 v[78:81], v[184:187], v[176:179], v[78:81]
	s_waitcnt lgkmcnt(2)
	v_mfma_f32_16x16x32_bf16 v[70:73], v[202:205], v[176:179], v[70:73]
	ds_read_b128 v[176:179], v161 offset:6144
	s_waitcnt lgkmcnt(2)
	v_mfma_f32_16x16x32_bf16 v[94:97], v[168:171], v[180:183], v[94:97]
	v_mfma_f32_16x16x32_bf16 v[82:85], v[172:175], v[180:183], v[82:85]
	v_mfma_f32_16x16x32_bf16 v[74:77], v[184:187], v[180:183], v[74:77]
	v_mfma_f32_16x16x32_bf16 v[66:69], v[202:205], v[180:183], v[66:69]
	ds_read_b128 v[180:183], v163
	s_waitcnt lgkmcnt(2)
	v_mfma_f32_16x16x32_bf16 v[30:33], v[168:171], v[206:209], v[30:33]
	v_mfma_f32_16x16x32_bf16 v[26:29], v[172:175], v[206:209], v[26:29]
	v_mfma_f32_16x16x32_bf16 v[22:25], v[184:187], v[206:209], v[22:25]
	v_mfma_f32_16x16x32_bf16 v[18:21], v[202:205], v[206:209], v[18:21]
	ds_read_b128 v[206:209], v163 offset:2048
	s_waitcnt lgkmcnt(2)
	v_mfma_f32_16x16x32_bf16 v[10:13], v[168:171], v[176:179], v[10:13]
	ds_read_b128 v[168:171], v164 offset:16384
	v_mfma_f32_16x16x32_bf16 v[6:9], v[172:175], v[176:179], v[6:9]
	ds_read_b128 v[172:175], v164 offset:18432
	v_mfma_f32_16x16x32_bf16 v[2:5], v[184:187], v[176:179], v[2:5]
	ds_read_b128 v[184:187], v164 offset:20480
	v_mfma_f32_16x16x32_bf16 v[14:17], v[202:205], v[176:179], v[14:17]
	ds_read_b128 v[202:205], v164 offset:22528
	ds_read_b128 v[176:179], v163 offset:4096
	s_waitcnt lgkmcnt(4)
	v_mfma_f32_16x16x32_bf16 v[90:93], v[168:171], v[180:183], v[90:93]
	s_waitcnt lgkmcnt(3)
	v_mfma_f32_16x16x32_bf16 v[86:89], v[172:175], v[180:183], v[86:89]
	s_waitcnt lgkmcnt(2)
	v_mfma_f32_16x16x32_bf16 v[78:81], v[184:187], v[180:183], v[78:81]
	s_waitcnt lgkmcnt(1)
	v_mfma_f32_16x16x32_bf16 v[70:73], v[202:205], v[180:183], v[70:73]
	ds_read_b128 v[180:183], v163 offset:6144
	s_waitcnt vmcnt(15)
	ds_write_b128 v160, v[34:37] offset:32768
	s_waitcnt vmcnt(14)
	ds_write_b128 v160, v[38:41] offset:49152
	s_waitcnt vmcnt(13)
	ds_write_b128 v160, v[42:45] offset:36864
	s_waitcnt vmcnt(12)
	ds_write_b128 v160, v[46:49] offset:53248
	s_waitcnt vmcnt(11)
	ds_write_b128 v160, v[50:53] offset:40960
	s_waitcnt vmcnt(10)
	ds_write_b128 v160, v[58:61] offset:57344
	s_waitcnt vmcnt(9)
	ds_write_b128 v160, v[54:57] offset:45056
	s_waitcnt vmcnt(8)
	ds_write_b128 v160, v[62:65] offset:61440
	v_lshl_add_u64 v[34:35], v[142:143], 0, s[74:75]
	v_lshl_add_u64 v[38:39], v[144:145], 0, s[74:75]
	s_addk_i32 s74, 0x180
	v_lshl_add_u64 v[42:43], v[146:147], 0, s[74:75]
	v_lshl_add_u64 v[46:47], v[148:149], 0, s[74:75]
	v_lshl_add_u64 v[50:51], v[150:151], 0, s[74:75]
	v_lshl_add_u64 v[54:55], v[152:153], 0, s[74:75]
	v_lshl_add_u64 v[56:57], v[154:155], 0, s[74:75]
	global_load_dwordx4 v[34:37], v[34:35], off offset:384
	v_lshl_add_u64 v[62:63], v[156:157], 0, s[74:75]
	global_load_dwordx4 v[38:41], v[38:39], off offset:384
	global_load_dwordx4 v[42:45], v[42:43], off
	global_load_dwordx4 v[46:49], v[46:47], off
	global_load_dwordx4 v[50:53], v[50:51], off
	global_load_dwordx4 v[58:61], v[54:55], off
	global_load_dwordx4 v[54:57], v[56:57], off
	global_load_dwordx4 v[62:65], v[62:63], off
	s_waitcnt lgkmcnt(0)
	s_barrier
	v_mfma_f32_16x16x32_bf16 v[94:97], v[168:171], v[206:209], v[94:97]
	v_mfma_f32_16x16x32_bf16 v[82:85], v[172:175], v[206:209], v[82:85]
	v_mfma_f32_16x16x32_bf16 v[74:77], v[184:187], v[206:209], v[74:77]
	v_mfma_f32_16x16x32_bf16 v[66:69], v[202:205], v[206:209], v[66:69]
	v_mfma_f32_16x16x32_bf16 v[30:33], v[168:171], v[176:179], v[30:33]
	v_mfma_f32_16x16x32_bf16 v[26:29], v[172:175], v[176:179], v[26:29]
	v_mfma_f32_16x16x32_bf16 v[22:25], v[184:187], v[176:179], v[22:25]
	v_mfma_f32_16x16x32_bf16 v[18:21], v[202:205], v[176:179], v[18:21]
	v_mfma_f32_16x16x32_bf16 v[10:13], v[168:171], v[180:183], v[10:13]
	v_mfma_f32_16x16x32_bf16 v[6:9], v[172:175], v[180:183], v[6:9]
	v_mfma_f32_16x16x32_bf16 v[2:5], v[184:187], v[180:183], v[2:5]
	v_mfma_f32_16x16x32_bf16 v[14:17], v[202:205], v[180:183], v[14:17]
	ds_read_b128 v[168:171], v162 offset:49152
	ds_read_b128 v[172:175], v161 offset:32768
	ds_read_b128 v[176:179], v162 offset:51200
	ds_read_b128 v[180:183], v162 offset:53248
	ds_read_b128 v[184:187], v162 offset:55296
	ds_read_b128 v[202:205], v161 offset:34816
	ds_read_b128 v[206:209], v161 offset:36864
	s_cmp_lt_u32 s0, 14
	s_waitcnt lgkmcnt(5)
	v_mfma_f32_16x16x32_bf16 v[90:93], v[168:171], v[172:175], v[90:93]
	s_waitcnt lgkmcnt(4)
	v_mfma_f32_16x16x32_bf16 v[86:89], v[176:179], v[172:175], v[86:89]
	s_waitcnt lgkmcnt(3)
	v_mfma_f32_16x16x32_bf16 v[78:81], v[180:183], v[172:175], v[78:81]
	s_waitcnt lgkmcnt(2)
	v_mfma_f32_16x16x32_bf16 v[70:73], v[184:187], v[172:175], v[70:73]
	ds_read_b128 v[172:175], v161 offset:38912
	s_waitcnt lgkmcnt(2)
	v_mfma_f32_16x16x32_bf16 v[94:97], v[168:171], v[202:205], v[94:97]
	v_mfma_f32_16x16x32_bf16 v[82:85], v[176:179], v[202:205], v[82:85]
	v_mfma_f32_16x16x32_bf16 v[74:77], v[180:183], v[202:205], v[74:77]
	v_mfma_f32_16x16x32_bf16 v[66:69], v[184:187], v[202:205], v[66:69]
	ds_read_b128 v[202:205], v163 offset:32768
	s_waitcnt lgkmcnt(2)
; __device__ __forceinline__ void lds_barrier() { asm volatile("s_waitcnt lgkmcnt(0)\n\ts_barrier" ::: "memory"); }
; template <bool PF2>
; __device__ __forceinline__ void gemm_mainloop_t(const bf16_t* __restrict__ A, int lda, const bf16_t* __restrict__ Bt, int ldb, int K,
;                                                 bf16_t* smem, f32x4 (&acc)[4][4], const int tid) {
;     ...
;     for (int kt = 0; kt < nk; kt += 2) {
;       gload(0, min(kt + 2, nk - 1));
;       __builtin_amdgcn_sched_barrier(0);
;       compute(0);
;       sstore(1, 1);
;       lds_barrier();
;       gload(1, min(kt + 3, nk - 1));
;       __builtin_amdgcn_sched_barrier(0);
;       compute(1);
;       sstore(0, 0);
;       lds_barrier();
;     }
; __device__ void phase_inproj(const Params& p, int l, unsigned char* smem) {
;     ...
;     const int rowb = mt * 128 + wm * 64 + fr;
;     const int colb = ct * 128 + wn * 64 + fq * 4;
; #pragma unroll
;     for (int mi = 0; mi < 4; ++mi) {
;       const f32x4 s0 = *(const f32x4*)(p.ssqn + (rowb + mi * 16) * 8), s1 = *(const f32x4*)(p.ssqn + (rowb + mi * 16) * 8 + 4);
;       const float rstd = rsqrtf(((s0[0] + s0[1]) + (s0[2] + s0[3]) + (s1[0] + s1[1]) + (s1[2] + s1[3])) * (1.f / 1024.f) + 1e-6f);
	v_mfma_f32_16x16x32_bf16 v[30:33], v[168:171], v[206:209], v[30:33]
	v_mfma_f32_16x16x32_bf16 v[26:29], v[176:179], v[206:209], v[26:29]
	v_mfma_f32_16x16x32_bf16 v[22:25], v[180:183], v[206:209], v[22:25]
	v_mfma_f32_16x16x32_bf16 v[18:21], v[184:187], v[206:209], v[18:21]
	ds_read_b128 v[206:209], v163 offset:34816
	s_waitcnt lgkmcnt(2)
	v_mfma_f32_16x16x32_bf16 v[10:13], v[168:171], v[172:175], v[10:13]
	ds_read_b128 v[168:171], v164 offset:49152
	v_mfma_f32_16x16x32_bf16 v[6:9], v[176:179], v[172:175], v[6:9]
	ds_read_b128 v[176:179], v164 offset:51200
	v_mfma_f32_16x16x32_bf16 v[2:5], v[180:183], v[172:175], v[2:5]
	ds_read_b128 v[180:183], v164 offset:53248
	v_mfma_f32_16x16x32_bf16 v[14:17], v[184:187], v[172:175], v[14:17]
	ds_read_b128 v[184:187], v164 offset:55296
	ds_read_b128 v[172:175], v163 offset:36864
	s_waitcnt lgkmcnt(4)
	v_mfma_f32_16x16x32_bf16 v[90:93], v[168:171], v[202:205], v[90:93]
	s_waitcnt lgkmcnt(3)
	v_mfma_f32_16x16x32_bf16 v[86:89], v[176:179], v[202:205], v[86:89]
	s_waitcnt lgkmcnt(2)
	v_mfma_f32_16x16x32_bf16 v[78:81], v[180:183], v[202:205], v[78:81]
	s_waitcnt lgkmcnt(1)
	v_mfma_f32_16x16x32_bf16 v[70:73], v[184:187], v[202:205], v[70:73]
	ds_read_b128 v[202:205], v163 offset:38912
	v_mfma_f32_16x16x32_bf16 v[94:97], v[168:171], v[206:209], v[94:97]
	v_mfma_f32_16x16x32_bf16 v[82:85], v[176:179], v[206:209], v[82:85]
	v_mfma_f32_16x16x32_bf16 v[74:77], v[180:183], v[206:209], v[74:77]
	v_mfma_f32_16x16x32_bf16 v[66:69], v[184:187], v[206:209], v[66:69]
	s_waitcnt lgkmcnt(1)
	v_mfma_f32_16x16x32_bf16 v[30:33], v[168:171], v[172:175], v[30:33]
	v_mfma_f32_16x16x32_bf16 v[26:29], v[176:179], v[172:175], v[26:29]
	v_mfma_f32_16x16x32_bf16 v[22:25], v[180:183], v[172:175], v[22:25]
	v_mfma_f32_16x16x32_bf16 v[18:21], v[184:187], v[172:175], v[18:21]
	s_waitcnt vmcnt(15)
	ds_write_b128 v160, v[98:101]
	s_waitcnt vmcnt(14)
	ds_write_b128 v160, v[102:105] offset:16384
	s_waitcnt vmcnt(13)
	ds_write_b128 v160, v[106:109] offset:4096
	s_waitcnt vmcnt(12)
	ds_write_b128 v160, v[110:113] offset:20480
	s_waitcnt lgkmcnt(4)
	v_mfma_f32_16x16x32_bf16 v[10:13], v[168:171], v[202:205], v[10:13]
	s_waitcnt vmcnt(11)
	ds_write_b128 v160, v[114:117] offset:8192
	s_waitcnt vmcnt(10)
	ds_write_b128 v160, v[118:121] offset:24576
	s_waitcnt vmcnt(9)
	ds_write_b128 v160, v[122:125] offset:12288
	s_waitcnt vmcnt(8)
	ds_write_b128 v160, v[126:129] offset:28672
	s_cbranch_scc0 .Lrot178_last
	s_add_i32 s1, s0, 4
	s_min_u32 s1, s1, 15
	s_lshl_b32 s74, s1, 7
	v_lshl_add_u64 v[98:99], v[142:143], 0, s[74:75]
	v_lshl_add_u64 v[102:103], v[144:145], 0, s[74:75]
	v_lshl_add_u64 v[106:107], v[146:147], 0, s[74:75]
	v_lshl_add_u64 v[110:111], v[148:149], 0, s[74:75]
	v_lshl_add_u64 v[114:115], v[150:151], 0, s[74:75]
	v_lshl_add_u64 v[118:119], v[152:153], 0, s[74:75]
	v_lshl_add_u64 v[122:123], v[154:155], 0, s[74:75]
	v_lshl_add_u64 v[126:127], v[156:157], 0, s[74:75]
	global_load_dwordx4 v[98:101], v[98:99], off
	s_add_i32 s0, s0, 2
	global_load_dwordx4 v[102:105], v[102:103], off
	global_load_dwordx4 v[106:109], v[106:107], off
	global_load_dwordx4 v[110:113], v[110:111], off
	global_load_dwordx4 v[114:117], v[114:115], off
	global_load_dwordx4 v[118:121], v[118:119], off
	global_load_dwordx4 v[122:125], v[122:123], off
	global_load_dwordx4 v[126:129], v[126:127], off
	s_waitcnt lgkmcnt(0)
	s_barrier
	v_mfma_f32_16x16x32_bf16 v[6:9], v[176:179], v[202:205], v[6:9]
	v_mfma_f32_16x16x32_bf16 v[2:5], v[180:183], v[202:205], v[2:5]
	v_mfma_f32_16x16x32_bf16 v[14:17], v[184:187], v[202:205], v[14:17]
	s_branch .Lrot178_body
.Lrot178_last:
	s_waitcnt lgkmcnt(0)
	s_barrier
	v_mfma_f32_16x16x32_bf16 v[6:9], v[176:179], v[202:205], v[6:9]
	v_mfma_f32_16x16x32_bf16 v[2:5], v[180:183], v[202:205], v[2:5]
	v_mfma_f32_16x16x32_bf16 v[14:17], v[184:187], v[202:205], v[14:17]
	v_lshl_add_u32 v102, s14, 7, v165
	s_waitcnt vmcnt(7)
	v_or_b32_e32 v34, v102, v159
	v_lshlrev_b32_e32 v36, 3, v34
	v_readlane_b32 s56, v253, 61
	v_ashrrev_i32_e32 v37, 31, v36
	v_readlane_b32 s70, v254, 11
	v_readlane_b32 s71, v254, 12
	s_mov_b32 s0, 0x358637bd
	v_mov_b64_e32 v[98:99], s[0:1]
	v_lshl_add_u64 v[100:101], v[36:37], 2, s[70:71]
	global_load_dwordx4 v[36:39], v[100:101], off offset:16
	global_load_dwordx4 v[40:43], v[100:101], off
	s_mov_b32 s2, 0x3a800000
	s_mov_b32 s0, 0x800000
	s_cmp_gt_i32 s12, 8
	v_readlane_b32 s57, v253, 62
	v_readlane_b32 s58, v253, 63
	v_readlane_b32 s59, v254, 0
	v_readlane_b32 s60, v254, 1
	v_readlane_b32 s61, v254, 2
	v_readlane_b32 s62, v254, 3
	v_readlane_b32 s63, v254, 4
	v_readlane_b32 s64, v254, 5
	v_readlane_b32 s65, v254, 6
	v_readlane_b32 s66, v254, 7
	v_readlane_b32 s67, v254, 8
	v_readlane_b32 s68, v254, 9
	v_readlane_b32 s69, v254, 10
	s_waitcnt vmcnt(0)
	v_mov_b32_e32 v44, v41
	v_mov_b32_e32 v45, v42
	v_mov_b32_e32 v41, v43
	v_pk_add_f32 v[44:45], v[44:45], v[40:41]
	v_mov_b32_e32 v40, v38
	v_mov_b32_e32 v41, v36
	v_mov_b32_e32 v36, v39
	v_pk_add_f32 v[46:47], v[40:41], v[36:37]
	global_load_dwordx4 v[36:39], v[100:101], off offset:528
	global_load_dwordx4 v[40:43], v[100:101], off offset:512
	s_waitcnt vmcnt(0)
; __device__ __forceinline__ void store4bf(bf16_t* p, f32x4 v) { u32x2 o; o.x = pack2(v[0], v[1]); o.y = pack2(v[2], v[3]); *(u32x2*)p = o; }
; __device__ void phase_inproj(const Params& p, int l, unsigned char* smem) {
;     ...
;     for (int mi = 0; mi < 4; ++mi) {
;       const f32x4 s0 = *(const f32x4*)(p.ssqn + (rowb + mi * 16) * 8), s1 = *(const f32x4*)(p.ssqn + (rowb + mi * 16) * 8 + 4);
;       const float rstd = rsqrtf(((s0[0] + s0[1]) + (s0[2] + s0[3]) + (s1[0] + s1[1]) + (s1[2] + s1[3])) * (1.f / 1024.f) + 1e-6f);
; #pragma unroll
;       for (int ni = 0; ni < 4; ++ni) acc[mi][ni] *= rstd;
;     }
;     if (ct < 9) {
; #pragma unroll
;       for (int mi = 0; mi < 4; ++mi)
; #pragma unroll
;         for (int ni = 0; ni < 4; ++ni) store4bf(p.qkvA + (size_t)(rowb + mi * 16) * 1152 + colb + ni * 16, acc[mi][ni]);
;     } else if (ct < 17) {
; #pragma unroll
;       for (int mi = 0; mi < 4; ++mi)
; #pragma unroll
;         for (int ni = 0; ni < 4; ++ni) store4bf(p.qkB + (size_t)(rowb + mi * 16) * 1024 + (colb - 1152) + ni * 16, acc[mi][ni]);
;     } else if (ct < 21) {
;     ...
;     } else {
;       if (wn == 0) {
	v_mov_b32_e32 v48, v41
	v_mov_b32_e32 v49, v42
	v_mov_b32_e32 v41, v43
	v_pk_add_f32 v[40:41], v[48:49], v[40:41]
	v_mov_b32_e32 v42, v38
	v_mov_b32_e32 v43, v36
	v_mov_b32_e32 v36, v39
	v_pk_add_f32 v[36:37], v[42:43], v[36:37]
	v_mov_b32_e32 v38, v40
	v_mov_b32_e32 v39, v44
	v_mov_b32_e32 v44, v41
	v_pk_add_f32 v[38:39], v[38:39], v[44:45]
	v_mov_b32_e32 v40, v37
	v_mov_b32_e32 v41, v47
	v_pk_add_f32 v[38:39], v[38:39], v[40:41]
	v_mov_b32_e32 v37, v46
	v_pk_add_f32 v[36:37], v[36:37], v[38:39]
	s_nop 0
	v_pk_fma_f32 v[36:37], v[36:37], s[2:3], v[98:99] op_sel_hi:[1,0,0]
	s_nop 0
	v_mul_f32_e32 v0, 0x4b800000, v37
	v_cmp_gt_f32_e64 s[8:9], s0, v37
	v_cmp_gt_f32_e32 vcc, s0, v36
	s_nop 0
	v_cndmask_b32_e64 v0, v37, v0, s[8:9]
	v_rsq_f32_e32 v0, v0
	s_nop 0
	v_mul_f32_e32 v35, 0x45800000, v0
	v_cndmask_b32_e64 v0, v0, v35, s[8:9]
	v_pk_mul_f32 v[64:65], v[92:93], v[0:1] op_sel_hi:[1,0]
	v_pk_mul_f32 v[90:91], v[90:91], v[0:1] op_sel_hi:[1,0]
	v_pk_mul_f32 v[60:61], v[88:89], v[0:1] op_sel_hi:[1,0]
	v_pk_mul_f32 v[62:63], v[86:87], v[0:1] op_sel_hi:[1,0]
	v_pk_mul_f32 v[56:57], v[80:81], v[0:1] op_sel_hi:[1,0]
	v_pk_mul_f32 v[58:59], v[78:79], v[0:1] op_sel_hi:[1,0]
	v_pk_mul_f32 v[52:53], v[72:73], v[0:1] op_sel_hi:[1,0]
	v_pk_mul_f32 v[54:55], v[70:71], v[0:1] op_sel_hi:[1,0]
	v_mul_f32_e32 v0, 0x4b800000, v36
	v_cndmask_b32_e32 v0, v36, v0, vcc
	v_rsq_f32_e32 v0, v0
	s_nop 0
	v_mul_f32_e32 v35, 0x45800000, v0
	v_cndmask_b32_e32 v0, v0, v35, vcc
	v_pk_mul_f32 v[36:37], v[68:69], v[0:1] op_sel_hi:[1,0]
	v_pk_mul_f32 v[38:39], v[66:67], v[0:1] op_sel_hi:[1,0]
	global_load_dwordx4 v[66:69], v[100:101], off offset:1040
	global_load_dwordx4 v[70:73], v[100:101], off offset:1024
	v_pk_mul_f32 v[42:43], v[74:75], v[0:1] op_sel_hi:[1,0]
	v_pk_mul_f32 v[40:41], v[76:77], v[0:1] op_sel_hi:[1,0]
	v_pk_mul_f32 v[48:49], v[96:97], v[0:1] op_sel_hi:[1,0]
	v_pk_mul_f32 v[50:51], v[94:95], v[0:1] op_sel_hi:[1,0]
	v_pk_mul_f32 v[44:45], v[84:85], v[0:1] op_sel_hi:[1,0]
	v_pk_mul_f32 v[46:47], v[82:83], v[0:1] op_sel_hi:[1,0]
	s_waitcnt vmcnt(0)
	v_mov_b32_e32 v74, v71
	v_mov_b32_e32 v75, v72
	v_mov_b32_e32 v71, v73
	v_pk_add_f32 v[74:75], v[74:75], v[70:71]
	v_mov_b32_e32 v70, v68
	v_mov_b32_e32 v71, v66
	v_mov_b32_e32 v66, v69
	v_pk_add_f32 v[76:77], v[70:71], v[66:67]
	global_load_dwordx4 v[66:69], v[100:101], off offset:1552
	global_load_dwordx4 v[70:73], v[100:101], off offset:1536
	s_waitcnt vmcnt(0)
	v_mov_b32_e32 v78, v71
	v_mov_b32_e32 v79, v72
	v_mov_b32_e32 v71, v73
	v_pk_add_f32 v[70:71], v[78:79], v[70:71]
	v_mov_b32_e32 v72, v68
	v_mov_b32_e32 v73, v66
	v_mov_b32_e32 v66, v69
	v_pk_add_f32 v[66:67], v[72:73], v[66:67]
	v_mov_b32_e32 v68, v70
	v_mov_b32_e32 v69, v74
	v_mov_b32_e32 v74, v71
	v_pk_add_f32 v[68:69], v[68:69], v[74:75]
	v_mov_b32_e32 v70, v67
	v_mov_b32_e32 v71, v77
	v_pk_add_f32 v[68:69], v[68:69], v[70:71]
	v_mov_b32_e32 v67, v76
	v_pk_add_f32 v[66:67], v[66:67], v[68:69]
	s_nop 0
	v_pk_fma_f32 v[66:67], v[66:67], s[2:3], v[98:99] op_sel_hi:[1,0,0]
	s_nop 0
	v_mul_f32_e32 v0, 0x4b800000, v67
	v_cmp_gt_f32_e64 s[8:9], s0, v67
	v_cmp_gt_f32_e32 vcc, s0, v66
	s_mov_b64 s[0:1], -1
	v_cndmask_b32_e64 v0, v67, v0, s[8:9]
	v_rsq_f32_e32 v0, v0
	s_nop 0
	v_mul_f32_e32 v35, 0x45800000, v0
	v_cndmask_b32_e64 v0, v0, v35, s[8:9]
	v_pk_mul_f32 v[32:33], v[32:33], v[0:1] op_sel_hi:[1,0]
	v_pk_mul_f32 v[30:31], v[30:31], v[0:1] op_sel_hi:[1,0]
	v_pk_mul_f32 v[28:29], v[28:29], v[0:1] op_sel_hi:[1,0]
	v_pk_mul_f32 v[26:27], v[26:27], v[0:1] op_sel_hi:[1,0]
	v_pk_mul_f32 v[24:25], v[24:25], v[0:1] op_sel_hi:[1,0]
	v_pk_mul_f32 v[22:23], v[22:23], v[0:1] op_sel_hi:[1,0]
	v_pk_mul_f32 v[20:21], v[20:21], v[0:1] op_sel_hi:[1,0]
	v_pk_mul_f32 v[18:19], v[18:19], v[0:1] op_sel_hi:[1,0]
	v_mul_f32_e32 v0, 0x4b800000, v66
	v_cndmask_b32_e32 v0, v66, v0, vcc
	v_rsq_f32_e32 v0, v0
	s_nop 0
	v_mul_f32_e32 v35, 0x45800000, v0
	v_cndmask_b32_e32 v0, v0, v35, vcc
	v_pk_mul_f32 v[12:13], v[12:13], v[0:1] op_sel_hi:[1,0]
	v_pk_mul_f32 v[68:69], v[10:11], v[0:1] op_sel_hi:[1,0]
	v_pk_mul_f32 v[8:9], v[8:9], v[0:1] op_sel_hi:[1,0]
	v_pk_mul_f32 v[66:67], v[6:7], v[0:1] op_sel_hi:[1,0]
	v_pk_mul_f32 v[6:7], v[4:5], v[0:1] op_sel_hi:[1,0]
	v_pk_mul_f32 v[10:11], v[2:3], v[0:1] op_sel_hi:[1,0]
	v_pk_mul_f32 v[2:3], v[16:17], v[0:1] op_sel_hi:[1,0]
	v_pk_mul_f32 v[4:5], v[14:15], v[0:1] op_sel_hi:[1,0]
	v_lshl_or_b32 v0, s12, 7, v167
	s_cbranch_scc0 .LBB0_249
	s_cmp_gt_u32 s12, 16
	s_cbranch_scc0 .LBB0_246
	s_cmp_gt_u32 s12, 20
	s_cbranch_scc0 .LBB0_243
	s_cmp_gt_u32 s12, 23
	s_cbranch_scc0 .LBB0_190
	s_cmp_gt_u32 s12, 47
	s_cbranch_scc0 .LBB0_187
	s_and_saveexec_b64 s[0:1], s[4:5]
	s_cbranch_execz .LBB0_186
; __device__ __forceinline__ void store4bf(bf16_t* p, f32x4 v) { u32x2 o; o.x = pack2(v[0], v[1]); o.y = pack2(v[2], v[3]); *(u32x2*)p = o; }
; __device__ void phase_inproj(const Params& p, int l, unsigned char* smem) {
;     ...
;       if (wn == 0) {
; #pragma unroll
;         for (int mi = 0; mi < 4; ++mi) {
;           const int row = rowb + mi * 16, pos = row & 8191;
;           const f32x4 c = *(const f32x4*)(p.ropec + pos * 16 + fq * 4), s = *(const f32x4*)(p.ropes + pos * 16 + fq * 4);
;           const f32x4 x1 = acc[mi][0], x2 = acc[mi][1];
;           const f32x4 o1 = x1 * c - x2 * s, o2 = x1 * s + x2 * c;
; #pragma unroll
;           for (int h = 0; h < 6; ++h) {
;             store4bf(p.kC + (size_t)row * 576 + h * 96 + 64 + fq * 4, o1);
;             store4bf(p.kC + (size_t)row * 576 + h * 96 + 80 + fq * 4, o2);
;           }
;         }
;       }
	v_lshlrev_b32_e32 v14, 6, v34
	v_and_b32_e32 v70, 0x7f3c0, v14
	v_mov_b32_e32 v71, v1
	v_lshl_add_u64 v[14:15], v[136:137], 0, v[70:71]
	v_lshl_add_u64 v[70:71], v[138:139], 0, v[70:71]
	global_load_dwordx4 v[70:73], v[70:71], off
	s_movk_i32 s8, 0x480
	global_load_dwordx4 v[14:17], v[14:15], off
	v_or_b32_e32 v35, 16, v34
	s_waitcnt vmcnt(1)
	v_pk_mul_f32 v[76:77], v[62:63], v[70:71]
	v_pk_mul_f32 v[70:71], v[90:91], v[70:71]
	v_pk_mul_f32 v[74:75], v[60:61], v[72:73]
	s_waitcnt vmcnt(0)
	v_pk_fma_f32 v[76:77], v[90:91], v[14:15], v[76:77] neg_lo:[0,0,1] neg_hi:[0,0,1]
	v_pk_mul_f32 v[72:73], v[64:65], v[72:73]
	v_pk_fma_f32 v[14:15], v[62:63], v[14:15], v[70:71]
	v_pk_fma_f32 v[74:75], v[64:65], v[16:17], v[74:75] neg_lo:[0,0,1] neg_hi:[0,0,1]
	v_pk_fma_f32 v[16:17], v[60:61], v[16:17], v[72:73]
	v_mad_i64_i32 v[70:71], s[2:3], v34, s8, v[140:141]
	v_cvt_pk_bf16_f32 v14, v14, v15
	v_cvt_pk_bf16_f32 v15, v16, v17
	v_cvt_pk_bf16_f32 v72, v76, v77
	v_cvt_pk_bf16_f32 v73, v74, v75
	global_store_dwordx2 v[70:71], v[72:73], off offset:128
	global_store_dwordx2 v[70:71], v[14:15], off offset:160
	global_store_dwordx2 v[70:71], v[72:73], off offset:320
	global_store_dwordx2 v[70:71], v[14:15], off offset:352
	global_store_dwordx2 v[70:71], v[72:73], off offset:512
	global_store_dwordx2 v[70:71], v[14:15], off offset:544
	global_store_dwordx2 v[70:71], v[72:73], off offset:704
	global_store_dwordx2 v[70:71], v[14:15], off offset:736
	global_store_dwordx2 v[70:71], v[72:73], off offset:896
	global_store_dwordx2 v[70:71], v[14:15], off offset:928
	global_store_dwordx2 v[70:71], v[72:73], off offset:1088
	global_store_dwordx2 v[70:71], v[14:15], off offset:1120
	v_lshlrev_b32_e32 v14, 6, v35
	v_and_b32_e32 v70, 0x7f7c0, v14
	v_mov_b32_e32 v71, v1
	v_lshl_add_u64 v[14:15], v[136:137], 0, v[70:71]
	v_lshl_add_u64 v[70:71], v[138:139], 0, v[70:71]
	global_load_dwordx4 v[70:73], v[70:71], off
	s_waitcnt vmcnt(0)
	v_pk_mul_f32 v[76:77], v[46:47], v[70:71]
	global_load_dwordx4 v[14:17], v[14:15], off
	v_pk_mul_f32 v[70:71], v[50:51], v[70:71]
	v_pk_mul_f32 v[74:75], v[44:45], v[72:73]
	v_pk_mul_f32 v[72:73], v[48:49], v[72:73]
	s_waitcnt vmcnt(0)
	v_pk_fma_f32 v[76:77], v[50:51], v[14:15], v[76:77] neg_lo:[0,0,1] neg_hi:[0,0,1]
	v_pk_fma_f32 v[14:15], v[46:47], v[14:15], v[70:71]
	v_pk_fma_f32 v[74:75], v[48:49], v[16:17], v[74:75] neg_lo:[0,0,1] neg_hi:[0,0,1]
	v_pk_fma_f32 v[16:17], v[44:45], v[16:17], v[72:73]
	v_mad_i64_i32 v[70:71], s[2:3], v35, s8, v[140:141]
	v_cvt_pk_bf16_f32 v14, v14, v15
	v_cvt_pk_bf16_f32 v15, v16, v17
	v_or_b32_e32 v35, 32, v34
	v_cvt_pk_bf16_f32 v72, v76, v77
	v_cvt_pk_bf16_f32 v73, v74, v75
	global_store_dwordx2 v[70:71], v[72:73], off offset:128
	global_store_dwordx2 v[70:71], v[14:15], off offset:160
	global_store_dwordx2 v[70:71], v[72:73], off offset:320
	global_store_dwordx2 v[70:71], v[14:15], off offset:352
	global_store_dwordx2 v[70:71], v[72:73], off offset:512
	global_store_dwordx2 v[70:71], v[14:15], off offset:544
	global_store_dwordx2 v[70:71], v[72:73], off offset:704
	global_store_dwordx2 v[70:71], v[14:15], off offset:736
	global_store_dwordx2 v[70:71], v[72:73], off offset:896
	global_store_dwordx2 v[70:71], v[14:15], off offset:928
	global_store_dwordx2 v[70:71], v[72:73], off offset:1088
	global_store_dwordx2 v[70:71], v[14:15], off offset:1120
	v_lshlrev_b32_e32 v14, 6, v35
	v_and_b32_e32 v70, 0x7fbc0, v14
	v_mov_b32_e32 v71, v1
	v_lshl_add_u64 v[14:15], v[136:137], 0, v[70:71]
	v_lshl_add_u64 v[70:71], v[138:139], 0, v[70:71]
	global_load_dwordx4 v[70:73], v[70:71], off
	s_waitcnt vmcnt(0)
	v_pk_mul_f32 v[76:77], v[26:27], v[70:71]
	global_load_dwordx4 v[14:17], v[14:15], off
	v_pk_mul_f32 v[70:71], v[30:31], v[70:71]
	v_pk_mul_f32 v[74:75], v[28:29], v[72:73]
	v_pk_mul_f32 v[72:73], v[32:33], v[72:73]
	s_waitcnt vmcnt(0)
	v_pk_fma_f32 v[76:77], v[30:31], v[14:15], v[76:77] neg_lo:[0,0,1] neg_hi:[0,0,1]
	v_pk_fma_f32 v[14:15], v[26:27], v[14:15], v[70:71]
	v_pk_fma_f32 v[74:75], v[32:33], v[16:17], v[74:75] neg_lo:[0,0,1] neg_hi:[0,0,1]
	v_pk_fma_f32 v[16:17], v[28:29], v[16:17], v[72:73]
	v_mad_i64_i32 v[70:71], s[2:3], v35, s8, v[140:141]
	v_cvt_pk_bf16_f32 v14, v14, v15
	v_cvt_pk_bf16_f32 v15, v16, v17
	v_or_b32_e32 v35, 48, v34
	v_cvt_pk_bf16_f32 v72, v76, v77
	v_cvt_pk_bf16_f32 v73, v74, v75
	global_store_dwordx2 v[70:71], v[72:73], off offset:128
	global_store_dwordx2 v[70:71], v[14:15], off offset:160
	global_store_dwordx2 v[70:71], v[72:73], off offset:320
	global_store_dwordx2 v[70:71], v[14:15], off offset:352
	global_store_dwordx2 v[70:71], v[72:73], off offset:512
	global_store_dwordx2 v[70:71], v[14:15], off offset:544
	global_store_dwordx2 v[70:71], v[72:73], off offset:704
	global_store_dwordx2 v[70:71], v[14:15], off offset:736
	global_store_dwordx2 v[70:71], v[72:73], off offset:896
	global_store_dwordx2 v[70:71], v[14:15], off offset:928
	global_store_dwordx2 v[70:71], v[72:73], off offset:1088
	global_store_dwordx2 v[70:71], v[14:15], off offset:1120
	v_lshlrev_b32_e32 v14, 6, v35
	v_and_b32_e32 v70, 0x7ffc0, v14
	v_mov_b32_e32 v71, v1
	v_lshl_add_u64 v[14:15], v[136:137], 0, v[70:71]
	v_lshl_add_u64 v[70:71], v[138:139], 0, v[70:71]
	global_load_dwordx4 v[70:73], v[70:71], off
	s_waitcnt vmcnt(0)
	v_pk_mul_f32 v[76:77], v[66:67], v[70:71]
	global_load_dwordx4 v[14:17], v[14:15], off
	v_pk_mul_f32 v[70:71], v[68:69], v[70:71]
	v_pk_mul_f32 v[74:75], v[8:9], v[72:73]
	v_pk_mul_f32 v[72:73], v[12:13], v[72:73]
	s_waitcnt vmcnt(0)
	v_pk_fma_f32 v[76:77], v[68:69], v[14:15], v[76:77] neg_lo:[0,0,1] neg_hi:[0,0,1]
	v_pk_fma_f32 v[14:15], v[66:67], v[14:15], v[70:71]
	v_pk_fma_f32 v[74:75], v[12:13], v[16:17], v[74:75] neg_lo:[0,0,1] neg_hi:[0,0,1]
	v_pk_fma_f32 v[16:17], v[8:9], v[16:17], v[72:73]
	v_mad_i64_i32 v[70:71], s[2:3], v35, s8, v[140:141]
	v_cvt_pk_bf16_f32 v14, v14, v15
	v_cvt_pk_bf16_f32 v15, v16, v17
	v_cvt_pk_bf16_f32 v72, v76, v77
	v_cvt_pk_bf16_f32 v73, v74, v75
	global_store_dwordx2 v[70:71], v[72:73], off offset:128
	global_store_dwordx2 v[70:71], v[14:15], off offset:160
	global_store_dwordx2 v[70:71], v[72:73], off offset:320
	global_store_dwordx2 v[70:71], v[14:15], off offset:352
	global_store_dwordx2 v[70:71], v[72:73], off offset:512
	global_store_dwordx2 v[70:71], v[14:15], off offset:544
	global_store_dwordx2 v[70:71], v[72:73], off offset:704
	global_store_dwordx2 v[70:71], v[14:15], off offset:736
	global_store_dwordx2 v[70:71], v[72:73], off offset:896
	global_store_dwordx2 v[70:71], v[14:15], off offset:928
	global_store_dwordx2 v[70:71], v[72:73], off offset:1088
	global_store_dwordx2 v[70:71], v[14:15], off offset:1120

; __device__ __forceinline__ f32x4 mfma16(bf16x8 a, bf16x8 b, f32x4 c) { return __builtin_amdgcn_mfma_f32_16x16x32_bf16(a, b, c, 0, 0, 0); }
; template <int DQK, int DV, int MODE> ...
;     ...
;       if (MODE == 1) {
;         need_mask = (kt * 64 + 63) > (qpos0 + w * 32);
;         const int dmin = (qpos0 + w * 32) - (kt * 64 + 63);
;         if (dmin >= 0) {
;           const float blo = bias_lds[min(dmin, 2047)], bhi = bias_lds[min(dmin + 94, 2047)];
;           if (((__float_as_uint(blo) ^ __float_as_uint(bhi)) & 31u) == 0u) { path = 0; cb = blo; }
;         }
;       }
;       constexpr int QG = (DV == 128) ? ATT_QG_B : 2;
; #pragma unroll
;       for (int q0 = 0; q0 < 2; q0 += QG) {
;         f32x4 S[QG][4];
; #pragma unroll
;         for (int t = 0; t < 4; ++t) {
;           {
;             const bf16x8 kf = *(const bf16x8*)(Ks + (t * 16 + fr) * KST + fq * 8);
; #pragma unroll
;             for (int qq = 0; qq < QG; ++qq) S[qq][t] = __builtin_amdgcn_mfma_f32_16x16x32_bf16(kf, *(const bf16x8*)(Qs2 + ((q0 + qq) * NKS) * 512), (f32x4){0.f, 0.f, 0.f, 0.f}, 0, 0, 0);
;           }
; #pragma unroll
;           for (int ks = 1; ks < NKS; ++ks) {
;             const bf16x8 kf = *(const bf16x8*)(Ks + (t * 16 + fr) * KST + ks * 32 + fq * 8);
; #pragma unroll
;             for (int qq = 0; qq < QG; ++qq) S[qq][t] = mfma16(kf, *(const bf16x8*)(Qs2 + ((q0 + qq) * NKS + ks) * 512), S[qq][t]);
;           }
;         }
.LBB0_535:
	v_cmp_le_i32_e32 vcc, s25, v227
	s_and_saveexec_b64 s[2:3], vcc
	s_cbranch_execz .LBB0_547
	ds_read_b128 v[166:169], v124
	ds_read_b128 v[174:177], v124 offset:2048
	ds_read_b128 v[110:113], v207
	ds_read_b128 v[170:173], v124 offset:1024
	ds_read_b128 v[178:181], v124 offset:3072
	ds_read_b128 v[182:185], v207 offset:64
	ds_read_b128 v[106:109], v207 offset:2560
	ds_read_b128 v[186:189], v207 offset:2624
	ds_read_b128 v[102:105], v207 offset:5120
	ds_read_b128 v[94:97], v207 offset:7680
	v_cmp_lt_i32_e32 vcc, -1, v232
	s_mov_b64 s[12:13], 0
	v_mov_b32_e32 v242, 0
	s_and_saveexec_b64 s[4:5], vcc
	s_cbranch_execz .LBB0_538
	v_min_u32_e32 v92, 0x7ff, v232
	v_min_u32_e32 v93, 0x7a1, v232
	v_lshl_add_u32 v92, v92, 2, 0
	v_lshl_add_u32 v93, v93, 2, 0
	ds_read_b32 v92, v92 offset:34816
	ds_read_b32 v93, v93 offset:35192
	s_waitcnt lgkmcnt(0)
	v_bitop3_b32 v93, v93, 31, v92 bitop3:0x48
	v_cmp_eq_u32_e32 vcc, 0, v93
	s_and_b64 s[12:13], vcc, exec
	s_nop 0
	v_cndmask_b32_e32 v242, 0, v92, vcc
.LBB0_538:
	s_or_b64 exec, exec, s[4:5]
	s_xor_b64 s[4:5], s[12:13], -1
	v_cmp_gt_i32_e32 vcc, s26, v226
	s_waitcnt lgkmcnt(7)
	v_mfma_f32_16x16x32_bf16 v[98:101], v[110:113], v[166:169], 0
	v_mfma_f32_16x16x32_bf16 v[110:113], v[110:113], v[174:177], 0
	s_waitcnt lgkmcnt(4)
	v_mfma_f32_16x16x32_bf16 v[98:101], v[182:185], v[170:173], v[98:101]
	v_mfma_f32_16x16x32_bf16 v[110:113], v[182:185], v[178:181], v[110:113]
	ds_read_b128 v[182:185], v207 offset:5184
	s_waitcnt lgkmcnt(4)
	v_mfma_f32_16x16x32_bf16 v[118:121], v[106:109], v[166:169], 0
	v_mfma_f32_16x16x32_bf16 v[106:109], v[106:109], v[174:177], 0
	s_waitcnt lgkmcnt(3)
	v_mfma_f32_16x16x32_bf16 v[118:121], v[186:189], v[170:173], v[118:121]
	v_mfma_f32_16x16x32_bf16 v[106:109], v[186:189], v[178:181], v[106:109]
	ds_read_b128 v[186:189], v207 offset:7744
	s_waitcnt lgkmcnt(3)
	v_mfma_f32_16x16x32_bf16 v[90:93], v[102:105], v[166:169], 0
	v_mfma_f32_16x16x32_bf16 v[102:105], v[102:105], v[174:177], 0
	s_waitcnt lgkmcnt(1)
	v_mfma_f32_16x16x32_bf16 v[90:93], v[182:185], v[170:173], v[90:93]
	v_mfma_f32_16x16x32_bf16 v[102:105], v[182:185], v[178:181], v[102:105]
	v_mfma_f32_16x16x32_bf16 v[114:117], v[94:97], v[166:169], 0
	v_mfma_f32_16x16x32_bf16 v[94:97], v[94:97], v[174:177], 0
	s_waitcnt lgkmcnt(0)
	v_mfma_f32_16x16x32_bf16 v[114:117], v[186:189], v[170:173], v[114:117]
	v_mfma_f32_16x16x32_bf16 v[94:97], v[186:189], v[178:181], v[94:97]
	v_add_u32_e32 v246, v222, v232
	s_and_saveexec_b64 s[12:13], s[4:5]
	s_xor_b64 s[20:21], exec, s[12:13]
	s_cbranch_execz .LBB0_540
	s_cbranch_vccz .Lb1a_q1
; __device__ __forceinline__ float fmax3(float a, float b, float c) { float r; asm("v_max3_f32 %0, %1, %2, %3" : "=v"(r) : "v"(a), "v"(b), "v"(c)); return r; }
; template <int DQK, int DV, int MODE> ...
;     ...
;             float mx = -1e30f;
; #pragma unroll
;             for (int t = 0; t < 4; ++t)
; #pragma unroll
;               for (int r = 0; r < 4; ++r) {
;                 const int j = kt * 64 + t * 16 + fq * 4 + r;
;                 float sx = S[qq][t][r] * c1;
;                 if (MODE == 1) {
;                   const int dist = qpos0 + qrow - j;
;                   sx += bias_lds[min(max(dist, 0), 2047)];
;                   if (need_mask && dist < 0) sx = -1e30f;
;                 } else if (MODE == 2) {
;                   if ((qpos0 + qrow - j) < 0) sx = -1e30f;
;                 } else {
;                   const int rel = 128 + qrow - j;
;                   sx += bias_lds[min(max(rel, 0), 128)];
;                   if (rel < 0 || rel > 128 || j < jmin) sx = -1e30f;
;                 }
;                 P[t][r] = sx;
;               }
; #pragma unroll
;             for (int t = 0; t < 4; ++t) { mx = fmax3(mx, P[t][0], P[t][1]); mx = fmax3(mx, P[t][2], P[t][3]); }
;             mx = xmax_rows(mx);
;             mn = fmax3(mrow[qi], mx, mx);
; #pragma unroll
;             for (int t = 0; t < 4; ++t) P[t] = P[t] - mn;
	v_add_u32_e32 v245, 63, v246
	v_add_u32_e32 v244, 62, v246
	v_add_u32_e32 v243, 61, v246
	v_add_u32_e32 v241, 60, v246
	v_add_u32_e32 v240, 47, v246
	v_add_u32_e32 v239, 46, v246
	v_add_u32_e32 v238, 45, v246
	v_add_u32_e32 v237, 44, v246
	v_add_u32_e32 v188, 31, v246
	v_add_u32_e32 v186, 30, v246
	v_add_u32_e32 v184, 29, v246
	v_add_u32_e32 v182, 28, v246
	v_med3_i32 v165, v245, 0, v198
	v_med3_i32 v166, v244, 0, v198
	v_med3_i32 v167, v243, 0, v198
	v_med3_i32 v168, v241, 0, v198
	v_med3_i32 v169, v240, 0, v198
	v_med3_i32 v170, v239, 0, v198
	v_med3_i32 v171, v238, 0, v198
	v_med3_i32 v172, v237, 0, v198
	v_lshl_add_u32 v165, v165, 2, 0
	v_lshl_add_u32 v166, v166, 2, 0
	v_lshl_add_u32 v167, v167, 2, 0
	v_lshl_add_u32 v168, v168, 2, 0
	v_lshl_add_u32 v169, v169, 2, 0
	v_lshl_add_u32 v170, v170, 2, 0
	v_lshl_add_u32 v171, v171, 2, 0
	v_lshl_add_u32 v172, v172, 2, 0
	ds_read_b32 v165, v165 offset:34816
	ds_read_b32 v166, v166 offset:34816
	ds_read_b32 v167, v167 offset:34816
	ds_read_b32 v168, v168 offset:34816
	ds_read_b32 v169, v169 offset:34816
	ds_read_b32 v170, v170 offset:34816
	ds_read_b32 v171, v171 offset:34816
	ds_read_b32 v172, v172 offset:34816
	v_cmp_gt_i32_e64 s[12:13], 0, v245
	s_waitcnt lgkmcnt(7)
	v_fmac_f32_e32 v165, 0x3e38aa3b, v98
	s_and_b64 s[12:13], vcc, s[12:13]
	v_cndmask_b32_e64 v98, v165, v194, s[12:13]
	v_cmp_gt_i32_e64 s[12:13], 0, v244
	s_waitcnt lgkmcnt(6)
	v_fmac_f32_e32 v166, 0x3e38aa3b, v99
	s_and_b64 s[12:13], vcc, s[12:13]
	v_cndmask_b32_e64 v99, v166, v194, s[12:13]
	v_cmp_gt_i32_e64 s[12:13], 0, v243
	s_waitcnt lgkmcnt(5)
	v_fmac_f32_e32 v167, 0x3e38aa3b, v100
	s_and_b64 s[12:13], vcc, s[12:13]
	v_cndmask_b32_e64 v100, v167, v194, s[12:13]
	v_cmp_gt_i32_e64 s[12:13], 0, v241
	s_waitcnt lgkmcnt(4)
	v_fmac_f32_e32 v168, 0x3e38aa3b, v101
	s_and_b64 s[12:13], vcc, s[12:13]
	v_cndmask_b32_e64 v101, v168, v194, s[12:13]
	v_cmp_gt_i32_e64 s[12:13], 0, v240
	s_waitcnt lgkmcnt(3)
	v_fmac_f32_e32 v169, 0x3e38aa3b, v118
	s_and_b64 s[12:13], vcc, s[12:13]
	v_cndmask_b32_e64 v118, v169, v194, s[12:13]
	v_cmp_gt_i32_e64 s[12:13], 0, v239
	s_waitcnt lgkmcnt(2)
	v_fmac_f32_e32 v170, 0x3e38aa3b, v119
	s_and_b64 s[12:13], vcc, s[12:13]
	v_cndmask_b32_e64 v119, v170, v194, s[12:13]
	v_cmp_gt_i32_e64 s[12:13], 0, v238
	s_waitcnt lgkmcnt(1)
	v_fmac_f32_e32 v171, 0x3e38aa3b, v120
	s_and_b64 s[12:13], vcc, s[12:13]
	v_cndmask_b32_e64 v120, v171, v194, s[12:13]
	v_cmp_gt_i32_e64 s[12:13], 0, v237
	s_waitcnt lgkmcnt(0)
	v_fmac_f32_e32 v172, 0x3e38aa3b, v121
	s_and_b64 s[12:13], vcc, s[12:13]
	v_add_u32_e32 v169, 15, v246
	v_add_u32_e32 v171, 14, v246
	v_add_u32_e32 v173, 13, v246
	v_add_u32_e32 v175, 12, v246
	v_cndmask_b32_e64 v121, v172, v194, s[12:13]
	v_med3_i32 v165, v188, 0, v198
	v_med3_i32 v166, v186, 0, v198
	v_med3_i32 v167, v184, 0, v198
	v_med3_i32 v168, v182, 0, v198
	v_med3_i32 v170, v169, 0, v198
	v_med3_i32 v172, v171, 0, v198
	v_med3_i32 v174, v173, 0, v198
	v_med3_i32 v176, v175, 0, v198
	v_lshl_add_u32 v165, v165, 2, 0
	v_lshl_add_u32 v166, v166, 2, 0
	v_lshl_add_u32 v167, v167, 2, 0
	v_lshl_add_u32 v168, v168, 2, 0
	v_lshl_add_u32 v170, v170, 2, 0
	v_lshl_add_u32 v172, v172, 2, 0
	v_lshl_add_u32 v174, v174, 2, 0
	v_lshl_add_u32 v176, v176, 2, 0
	ds_read_b32 v165, v165 offset:34816
	ds_read_b32 v166, v166 offset:34816
	ds_read_b32 v167, v167 offset:34816
	ds_read_b32 v168, v168 offset:34816
	ds_read_b32 v170, v170 offset:34816
	ds_read_b32 v172, v172 offset:34816
	ds_read_b32 v174, v174 offset:34816
	ds_read_b32 v176, v176 offset:34816
	v_cmp_gt_i32_e64 s[12:13], 0, v188
	s_waitcnt lgkmcnt(7)
	v_fmac_f32_e32 v165, 0x3e38aa3b, v90
	s_and_b64 s[12:13], vcc, s[12:13]
	v_cndmask_b32_e64 v90, v165, v194, s[12:13]
	v_cmp_gt_i32_e64 s[12:13], 0, v186
	s_waitcnt lgkmcnt(6)
	v_fmac_f32_e32 v166, 0x3e38aa3b, v91
	s_and_b64 s[12:13], vcc, s[12:13]
	v_cndmask_b32_e64 v91, v166, v194, s[12:13]
	v_cmp_gt_i32_e64 s[12:13], 0, v184
	s_waitcnt lgkmcnt(5)
	v_fmac_f32_e32 v167, 0x3e38aa3b, v92
	s_and_b64 s[12:13], vcc, s[12:13]
	v_cndmask_b32_e64 v92, v167, v194, s[12:13]
	v_cmp_gt_i32_e64 s[12:13], 0, v182
	s_waitcnt lgkmcnt(4)
	v_fmac_f32_e32 v168, 0x3e38aa3b, v93
	s_and_b64 s[12:13], vcc, s[12:13]
	v_cndmask_b32_e64 v93, v168, v194, s[12:13]
	v_cmp_gt_i32_e64 s[12:13], 0, v169
	s_waitcnt lgkmcnt(3)
	v_fmac_f32_e32 v170, 0x3e38aa3b, v114
	s_and_b64 s[12:13], vcc, s[12:13]
	v_max3_f32 v165, v194, v98, v99
	v_cndmask_b32_e64 v114, v170, v194, s[12:13]
	v_cmp_gt_i32_e64 s[12:13], 0, v171
	v_max3_f32 v165, v165, v100, v101
	s_waitcnt lgkmcnt(2)
	v_fmac_f32_e32 v172, 0x3e38aa3b, v115
	s_and_b64 s[12:13], vcc, s[12:13]
	v_max3_f32 v165, v165, v118, v119
	v_cndmask_b32_e64 v115, v172, v194, s[12:13]
	v_cmp_gt_i32_e64 s[12:13], 0, v173
	v_max3_f32 v165, v165, v120, v121
	s_waitcnt lgkmcnt(1)
	v_fmac_f32_e32 v174, 0x3e38aa3b, v116
	s_and_b64 s[12:13], vcc, s[12:13]
	v_max3_f32 v165, v165, v90, v91
	v_cndmask_b32_e64 v116, v174, v194, s[12:13]
	v_cmp_gt_i32_e64 s[12:13], 0, v175
	v_max3_f32 v165, v165, v92, v93
	s_waitcnt lgkmcnt(0)
	v_fmac_f32_e32 v176, 0x3e38aa3b, v117
	s_and_b64 s[12:13], vcc, s[12:13]
	v_max3_f32 v165, v165, v114, v115
	v_cndmask_b32_e64 v117, v176, v194, s[12:13]
	v_max3_f32 v165, v165, v116, v117
	s_nop 0
	v_mov_b32_e32 v166, v165
	s_nop 1
	v_permlane16_swap_b32_e32 v165, v166
	v_max3_f32 v165, v165, v166, v166
	s_nop 0
	v_mov_b32_e32 v166, v165
	s_nop 1
	v_permlane32_swap_b32_e32 v165, v166
	v_max3_f32 v165, v165, v166, v166
	s_nop 0
	v_max3_f32 v165, v236, v165, v165
	s_nop 0
	v_sub_f32_e32 v176, v98, v165
	v_sub_f32_e32 v177, v99, v165
	v_sub_f32_e32 v172, v100, v165
	v_sub_f32_e32 v173, v101, v165
	v_sub_f32_e32 v166, v118, v165
	v_sub_f32_e32 v167, v119, v165
	v_sub_f32_e32 v174, v120, v165
	v_sub_f32_e32 v175, v121, v165
	v_sub_f32_e32 v170, v90, v165
	v_sub_f32_e32 v171, v91, v165
	v_sub_f32_e32 v180, v92, v165
	v_sub_f32_e32 v181, v93, v165
	v_sub_f32_e32 v178, v114, v165
	v_sub_f32_e32 v179, v115, v165
	v_sub_f32_e32 v168, v116, v165
	v_sub_f32_e32 v169, v117, v165

; __device__ __forceinline__ float bflo(unsigned u) { return __uint_as_float(u << 16); }
; template <bool PF2>
; __device__ __forceinline__ void gemm_mainloop_t(const bf16_t* __restrict__ A, int lda, const bf16_t* __restrict__ Bt, int ldb, int K,
;                                                 bf16_t* smem, f32x4 (&acc)[4][4], const int tid) {
;     ...
;   auto compute = [&](int st) {
;     const bf16_t* as = smem + st * 2 * GSTAGE;
;     const bf16_t* bs = as + GSTAGE;
; #pragma unroll
;     for (int ks = 0; ks < 2; ++ks) {
;       bf16x8 af[4], bfr[4];
; #pragma unroll
;       for (int mi = 0; mi < 4; ++mi) af[mi] = *(const bf16x8*)(as + (wm * 64 + mi * 16 + fr) * GS + (((ks * 4 + fq) ^ (fr & 7)) * 8));
; #pragma unroll
;       for (int ni = 0; ni < 4; ++ni) bfr[ni] = *(const bf16x8*)(bs + (wn * 64 + ni * 16 + fr) * GS + (((ks * 4 + fq) ^ (fr & 7)) * 8));
; #pragma unroll
;       for (int mi = 0; mi < 4; ++mi)
; #pragma unroll
;         for (int ni = 0; ni < 4; ++ni) acc[mi][ni] = mfma16(bfr[ni], af[mi], acc[mi][ni]);
;     }
;   };
;   if (PF2) {
;     gload(0, 0);
;     gload(1, 1);
;     sstore(0, 0);
;     lds_barrier();
;     for (int kt = 0; kt < nk; kt += 2) {
;       gload(0, min(kt + 2, nk - 1));
;       __builtin_amdgcn_sched_barrier(0);
;       compute(0);
;       sstore(1, 1);
;       lds_barrier();
;       gload(1, min(kt + 3, nk - 1));
;       __builtin_amdgcn_sched_barrier(0);
;       compute(1);
;       sstore(0, 0);
;       lds_barrier();
;     }
;   } else {
;     gload(0, 0); sstore(0, 0);
;     lds_barrier();
;     for (int kt = 0; kt < nk; ++kt) {
;       gload(0, min(kt + 1, nk - 1));
;       __builtin_amdgcn_sched_barrier(0);
;       compute(kt & 1);
;       __builtin_amdgcn_sched_barrier(0);
;       sstore(0, (kt + 1) & 1);
;       lds_barrier();
;     }
; __device__ void phase_branch(const Params& p, int l, unsigned char* smem) {
;     ...
;       for (int mi = 0; mi < 4; ++mi)
; #pragma unroll
;         for (int ni = 0; ni < 4; ++ni) gg[mi][ni] = *(const u32x2*)(p.gates + (size_t)(rowb + mi * 16) * 3072 + seg * 1024 + colb + ni * 16);
; #pragma unroll
;       for (int mi = 0; mi < 4; ++mi)
; #pragma unroll
;         for (int ni = 0; ni < 4; ++ni) {
;           const u32x2 g = gg[mi][ni];
;           float t0 = bflo(g.x) * acc[mi][ni][0], t1 = bfhi(g.x) * acc[mi][ni][1], t2 = bflo(g.y) * acc[mi][ni][2], t3 = bfhi(g.y) * acc[mi][ni][3];
.LBB0_839:
	s_add_i32 s8, s8, 1
	s_min_i32 s10, s8, s9
	s_lshl_b32 s10, s10, 6
	s_ashr_i32 s11, s10, 31
	s_lshl_b64 s[10:11], s[10:11], 1
	v_lshl_add_u64 v[142:143], v[126:127], 0, s[10:11]
	v_lshl_add_u64 v[146:147], v[128:129], 0, s[10:11]
	v_lshl_add_u64 v[150:151], v[130:131], 0, s[10:11]
	v_lshl_add_u64 v[154:155], v[132:133], 0, s[10:11]
	v_lshl_add_u64 v[164:165], v[134:135], 0, s[10:11]
	v_lshl_add_u64 v[168:169], v[136:137], 0, s[10:11]
	v_lshl_add_u64 v[172:173], v[138:139], 0, s[10:11]
	v_lshl_add_u64 v[176:177], v[140:141], 0, s[10:11]
	global_load_dwordx4 v[142:145], v[142:143], off
	s_nop 0
	global_load_dwordx4 v[146:149], v[146:147], off
	s_nop 0
	global_load_dwordx4 v[150:153], v[150:151], off
	s_nop 0
	global_load_dwordx4 v[154:157], v[154:155], off
	s_nop 0
	global_load_dwordx4 v[164:167], v[164:165], off
	s_nop 0
	global_load_dwordx4 v[168:171], v[168:169], off
	s_nop 0
	global_load_dwordx4 v[172:175], v[172:173], off
	s_nop 0
	global_load_dwordx4 v[176:179], v[176:177], off
	s_and_b32 s10, s7, 0x4000
	s_lshl_b32 s10, s10, 1
	s_add_i32 s10, s10, 0
	v_lshl_add_u32 v0, v160, 1, s10
	v_add_u32_e32 v188, v0, v162
	v_add_u32_e32 v0, v0, v163
	ds_read_b128 v[180:183], v0 offset:16384
	ds_read_b128 v[184:187], v188
	ds_read_b128 v[204:207], v0 offset:18432
	ds_read_b128 v[208:211], v0 offset:20480
	ds_read_b128 v[212:215], v0 offset:22528
	ds_read_b128 v[216:219], v188 offset:2048
	ds_read_b128 v[220:223], v188 offset:4096
	ds_read_b128 v[224:227], v188 offset:6144
	v_lshl_add_u32 v0, v161, 1, s10
	v_add_u32_e32 v188, v0, v162
	v_add_u32_e32 v0, v0, v163
	s_waitcnt lgkmcnt(6)
	v_mfma_f32_16x16x32_bf16 v[62:65], v[180:183], v[184:187], v[62:65]
	s_waitcnt lgkmcnt(5)
	v_mfma_f32_16x16x32_bf16 v[58:61], v[204:207], v[184:187], v[58:61]
	s_waitcnt lgkmcnt(4)
	v_mfma_f32_16x16x32_bf16 v[54:57], v[208:211], v[184:187], v[54:57]
	s_waitcnt lgkmcnt(3)
	v_mfma_f32_16x16x32_bf16 v[50:53], v[212:215], v[184:187], v[50:53]
	ds_read_b128 v[184:187], v188
	s_waitcnt lgkmcnt(3)
	v_mfma_f32_16x16x32_bf16 v[46:49], v[180:183], v[216:219], v[46:49]
	v_mfma_f32_16x16x32_bf16 v[42:45], v[204:207], v[216:219], v[42:45]
	v_mfma_f32_16x16x32_bf16 v[38:41], v[208:211], v[216:219], v[38:41]
	v_mfma_f32_16x16x32_bf16 v[34:37], v[212:215], v[216:219], v[34:37]
	ds_read_b128 v[216:219], v188 offset:2048
	s_waitcnt lgkmcnt(3)
	v_mfma_f32_16x16x32_bf16 v[30:33], v[180:183], v[220:223], v[30:33]
	v_mfma_f32_16x16x32_bf16 v[26:29], v[204:207], v[220:223], v[26:29]
	v_mfma_f32_16x16x32_bf16 v[22:25], v[208:211], v[220:223], v[22:25]
	v_mfma_f32_16x16x32_bf16 v[18:21], v[212:215], v[220:223], v[18:21]
	ds_read_b128 v[220:223], v188 offset:4096
	s_waitcnt lgkmcnt(3)
	v_mfma_f32_16x16x32_bf16 v[14:17], v[180:183], v[224:227], v[14:17]
	ds_read_b128 v[180:183], v0 offset:16384
	v_mfma_f32_16x16x32_bf16 v[10:13], v[204:207], v[224:227], v[10:13]
	ds_read_b128 v[204:207], v0 offset:18432
	v_mfma_f32_16x16x32_bf16 v[6:9], v[208:211], v[224:227], v[6:9]
	ds_read_b128 v[208:211], v0 offset:20480
	v_mfma_f32_16x16x32_bf16 v[2:5], v[212:215], v[224:227], v[2:5]
	ds_read_b128 v[212:215], v0 offset:22528
	ds_read_b128 v[224:227], v188 offset:6144
	s_waitcnt lgkmcnt(4)
	v_mfma_f32_16x16x32_bf16 v[62:65], v[180:183], v[184:187], v[62:65]
	s_waitcnt lgkmcnt(3)
	v_mfma_f32_16x16x32_bf16 v[58:61], v[204:207], v[184:187], v[58:61]
	s_waitcnt lgkmcnt(2)
	v_mfma_f32_16x16x32_bf16 v[54:57], v[208:211], v[184:187], v[54:57]
	s_waitcnt lgkmcnt(1)
	v_mfma_f32_16x16x32_bf16 v[50:53], v[212:215], v[184:187], v[50:53]
	v_mfma_f32_16x16x32_bf16 v[46:49], v[180:183], v[216:219], v[46:49]
	v_mfma_f32_16x16x32_bf16 v[42:45], v[204:207], v[216:219], v[42:45]
	v_mfma_f32_16x16x32_bf16 v[38:41], v[208:211], v[216:219], v[38:41]
	v_mfma_f32_16x16x32_bf16 v[34:37], v[212:215], v[216:219], v[34:37]
	v_mfma_f32_16x16x32_bf16 v[30:33], v[180:183], v[220:223], v[30:33]
	v_mfma_f32_16x16x32_bf16 v[26:29], v[204:207], v[220:223], v[26:29]
	v_mfma_f32_16x16x32_bf16 v[22:25], v[208:211], v[220:223], v[22:25]
	v_mfma_f32_16x16x32_bf16 v[18:21], v[212:215], v[220:223], v[18:21]
	s_waitcnt lgkmcnt(0)
	v_mfma_f32_16x16x32_bf16 v[14:17], v[180:183], v[224:227], v[14:17]
	v_mfma_f32_16x16x32_bf16 v[10:13], v[204:207], v[224:227], v[10:13]
	v_mfma_f32_16x16x32_bf16 v[6:9], v[208:211], v[224:227], v[6:9]
	v_mfma_f32_16x16x32_bf16 v[2:5], v[212:215], v[224:227], v[2:5]
	s_addk_i32 s7, 0x4000
	s_and_b32 s10, s7, 0x4000
	v_lshl_add_u32 v0, s10, 1, v159
	s_waitcnt vmcnt(7)
	ds_write_b128 v0, v[142:145]
	s_waitcnt vmcnt(6)
	ds_write_b128 v0, v[146:149] offset:16384
	s_waitcnt vmcnt(5)
	ds_write_b128 v0, v[150:153] offset:4096
	s_waitcnt vmcnt(4)
	ds_write_b128 v0, v[154:157] offset:20480
	s_waitcnt vmcnt(3)
	ds_write_b128 v0, v[164:167] offset:8192
	s_waitcnt vmcnt(2)
	ds_write_b128 v0, v[168:171] offset:24576
	s_waitcnt vmcnt(1)
	ds_write_b128 v0, v[172:175] offset:12288
	s_waitcnt vmcnt(0)
	ds_write_b128 v0, v[176:179] offset:28672
	s_waitcnt lgkmcnt(0)
	s_barrier
	s_cmp_lg_u32 s6, s8
	s_cbranch_scc1 .LBB0_839
	s_lshl_b32 s74, s3, 11
	v_lshl_add_u64 v[126:127], v[124:125], 0, s[74:75]
	v_lshl_add_u64 v[128:129], v[126:127], 0, v[114:115]
	global_load_dwordx2 v[164:165], v[128:129], off
	global_load_dwordx2 v[154:155], v[128:129], off offset:32
	global_load_dwordx2 v[152:153], v[128:129], off offset:64
	global_load_dwordx2 v[150:151], v[128:129], off offset:96
	v_lshl_add_u64 v[128:129], v[126:127], 0, v[116:117]
	global_load_dwordx2 v[148:149], v[128:129], off
	global_load_dwordx2 v[146:147], v[128:129], off offset:32
	global_load_dwordx2 v[144:145], v[128:129], off offset:64
	global_load_dwordx2 v[142:143], v[128:129], off offset:96
	v_lshl_add_u64 v[128:129], v[126:127], 0, v[118:119]
	v_lshl_add_u64 v[126:127], v[126:127], 0, v[120:121]
	global_load_dwordx2 v[140:141], v[128:129], off
	global_load_dwordx2 v[138:139], v[128:129], off offset:32
	global_load_dwordx2 v[136:137], v[128:129], off offset:64
	global_load_dwordx2 v[134:135], v[128:129], off offset:96
	global_load_dwordx2 v[132:133], v[126:127], off
	global_load_dwordx2 v[130:131], v[126:127], off offset:32
	s_nop 0
	global_load_dwordx2 v[128:129], v[126:127], off offset:64
	s_nop 0
	global_load_dwordx2 v[126:127], v[126:127], off offset:96
	v_cndmask_b32_e64 v0, 0, 1, s[0:1]
	v_cmp_ne_u32_e64 s[6:7], 1, v0
	s_andn2_b64 vcc, exec, s[0:1]
	s_waitcnt vmcnt(15)
	v_lshlrev_b32_e32 v156, 16, v164
	v_and_b32_e32 v157, 0xffff0000, v164
	v_pk_mul_f32 v[156:157], v[62:63], v[156:157]
	v_lshlrev_b32_e32 v62, 16, v165
	v_and_b32_e32 v63, 0xffff0000, v165
	v_pk_mul_f32 v[62:63], v[64:65], v[62:63]
	s_cbranch_vccnz .LBB0_842
	v_lshlrev_b32_e32 v64, 16, v84
	v_and_b32_e32 v65, 0xffff0000, v84
	v_pk_add_f32 v[156:157], v[156:157], v[64:65]
	v_lshlrev_b32_e32 v64, 16, v85
	v_and_b32_e32 v65, 0xffff0000, v85
	v_pk_add_f32 v[62:63], v[62:63], v[64:65]

; __device__ __forceinline__ f32x4 mfma16(bf16x8 a, bf16x8 b, f32x4 c) { return __builtin_amdgcn_mfma_f32_16x16x32_bf16(a, b, c, 0, 0, 0); }
; __device__ __forceinline__ void lds_barrier() { asm volatile("s_waitcnt lgkmcnt(0)\n\ts_barrier" ::: "memory"); }
; template <bool PF2>
; __device__ __forceinline__ void gemm_mainloop_t(const bf16_t* __restrict__ A, int lda, const bf16_t* __restrict__ Bt, int ldb, int K,
;                                                 bf16_t* smem, f32x4 (&acc)[4][4], const int tid) {
;     ...
;   auto compute = [&](int st) {
;     const bf16_t* as = smem + st * 2 * GSTAGE;
;     const bf16_t* bs = as + GSTAGE;
; #pragma unroll
;     for (int ks = 0; ks < 2; ++ks) {
;       bf16x8 af[4], bfr[4];
; #pragma unroll
;       for (int mi = 0; mi < 4; ++mi) af[mi] = *(const bf16x8*)(as + (wm * 64 + mi * 16 + fr) * GS + (((ks * 4 + fq) ^ (fr & 7)) * 8));
; #pragma unroll
;       for (int ni = 0; ni < 4; ++ni) bfr[ni] = *(const bf16x8*)(bs + (wn * 64 + ni * 16 + fr) * GS + (((ks * 4 + fq) ^ (fr & 7)) * 8));
; #pragma unroll
;       for (int mi = 0; mi < 4; ++mi)
; #pragma unroll
;         for (int ni = 0; ni < 4; ++ni) acc[mi][ni] = mfma16(bfr[ni], af[mi], acc[mi][ni]);
;     }
;   };
;   if (PF2) {
;     gload(0, 0);
;     gload(1, 1);
;     sstore(0, 0);
;     lds_barrier();
;     for (int kt = 0; kt < nk; kt += 2) {
;       gload(0, min(kt + 2, nk - 1));
;       __builtin_amdgcn_sched_barrier(0);
;       compute(0);
;       sstore(1, 1);
;       lds_barrier();
;       gload(1, min(kt + 3, nk - 1));
;       __builtin_amdgcn_sched_barrier(0);
;       compute(1);
;       sstore(0, 0);
;       lds_barrier();
;     }
.LBB0_920:
	s_add_i32 s7, s6, 4
	s_min_u32 s7, s7, 15
	s_lshl_b32 s74, s7, 7
	v_lshl_add_u64 v[94:95], v[134:135], 0, s[74:75]
	v_lshl_add_u64 v[98:99], v[136:137], 0, s[74:75]
	v_lshl_add_u64 v[102:103], v[144:145], 0, s[74:75]
	v_lshl_add_u64 v[106:107], v[138:139], 0, s[74:75]
	v_lshl_add_u64 v[114:115], v[146:147], 0, s[74:75]
	v_lshl_add_u64 v[118:119], v[140:141], 0, s[74:75]
	v_lshl_add_u64 v[122:123], v[148:149], 0, s[74:75]
	v_lshl_add_u64 v[126:127], v[142:143], 0, s[74:75]
	global_load_dwordx4 v[94:97], v[94:95], off
	s_add_i32 s6, s6, 2
	global_load_dwordx4 v[98:101], v[98:99], off
	s_nop 0
	global_load_dwordx4 v[102:105], v[102:103], off
	s_nop 0
	global_load_dwordx4 v[106:109], v[106:107], off
	s_nop 0
	global_load_dwordx4 v[114:117], v[114:115], off
	s_nop 0
	global_load_dwordx4 v[118:121], v[118:119], off
	s_nop 0
	global_load_dwordx4 v[122:125], v[122:123], off
	s_nop 0
	global_load_dwordx4 v[126:129], v[126:127], off
	ds_read_b128 v[158:161], v153 offset:16384
	ds_read_b128 v[162:165], v153 offset:18432
	ds_read_b128 v[166:169], v152
	ds_read_b128 v[170:173], v152 offset:2048
	ds_read_b128 v[174:177], v153 offset:20480
	ds_read_b128 v[178:181], v153 offset:22528
	s_min_u32 s7, s6, 12
	s_waitcnt lgkmcnt(3)
	v_mfma_f32_16x16x32_bf16 v[110:113], v[158:161], v[166:169], v[110:113]
	s_lshl_b32 s74, s7, 7
	v_mfma_f32_16x16x32_bf16 v[90:93], v[162:165], v[166:169], v[90:93]
	s_waitcnt lgkmcnt(1)
	v_mfma_f32_16x16x32_bf16 v[82:85], v[174:177], v[166:169], v[82:85]
	s_waitcnt lgkmcnt(0)
	v_mfma_f32_16x16x32_bf16 v[62:65], v[178:181], v[166:169], v[62:65]
	v_mfma_f32_16x16x32_bf16 v[46:49], v[158:161], v[170:173], v[46:49]
	v_mfma_f32_16x16x32_bf16 v[42:45], v[162:165], v[170:173], v[42:45]
	v_mfma_f32_16x16x32_bf16 v[38:41], v[174:177], v[170:173], v[38:41]
	v_mfma_f32_16x16x32_bf16 v[34:37], v[178:181], v[170:173], v[34:37]
	ds_read_b128 v[166:169], v152 offset:4096
	ds_read_b128 v[170:173], v152 offset:6144
	s_waitcnt lgkmcnt(1)
	v_mfma_f32_16x16x32_bf16 v[30:33], v[158:161], v[166:169], v[30:33]
	v_mfma_f32_16x16x32_bf16 v[26:29], v[162:165], v[166:169], v[26:29]
	v_mfma_f32_16x16x32_bf16 v[22:25], v[174:177], v[166:169], v[22:25]
	v_mfma_f32_16x16x32_bf16 v[18:21], v[178:181], v[166:169], v[18:21]
	s_waitcnt lgkmcnt(0)
	v_mfma_f32_16x16x32_bf16 v[14:17], v[158:161], v[170:173], v[14:17]
	v_mfma_f32_16x16x32_bf16 v[10:13], v[162:165], v[170:173], v[10:13]
	ds_read_b128 v[158:161], v155 offset:16384
	ds_read_b128 v[162:165], v155 offset:18432
	v_mfma_f32_16x16x32_bf16 v[2:5], v[174:177], v[170:173], v[2:5]
	v_mfma_f32_16x16x32_bf16 v[6:9], v[178:181], v[170:173], v[6:9]
	ds_read_b128 v[166:169], v154
	ds_read_b128 v[170:173], v154 offset:2048
	ds_read_b128 v[174:177], v155 offset:20480
	ds_read_b128 v[178:181], v155 offset:22528
	s_waitcnt lgkmcnt(3)
	v_mfma_f32_16x16x32_bf16 v[110:113], v[158:161], v[166:169], v[110:113]
	v_mfma_f32_16x16x32_bf16 v[90:93], v[162:165], v[166:169], v[90:93]
	s_waitcnt lgkmcnt(1)
	v_mfma_f32_16x16x32_bf16 v[82:85], v[174:177], v[166:169], v[82:85]
	s_waitcnt lgkmcnt(0)
	v_mfma_f32_16x16x32_bf16 v[62:65], v[178:181], v[166:169], v[62:65]
	ds_read_b128 v[166:169], v154 offset:4096
	ds_read_b128 v[182:185], v154 offset:6144
	s_waitcnt vmcnt(15)
	ds_write_b128 v151, v[54:57] offset:32768
	s_waitcnt vmcnt(14)
	ds_write_b128 v151, v[50:53] offset:49152
	s_waitcnt vmcnt(13)
	ds_write_b128 v151, v[74:77] offset:36864
	s_waitcnt vmcnt(12)
	ds_write_b128 v151, v[58:61] offset:53248
	s_waitcnt vmcnt(11)
	ds_write_b128 v151, v[86:89] offset:40960
	s_waitcnt vmcnt(10)
	ds_write_b128 v151, v[66:69] offset:57344
	s_waitcnt vmcnt(9)
	ds_write_b128 v151, v[78:81] offset:45056
	s_waitcnt vmcnt(8)
	ds_write_b128 v151, v[70:73] offset:61440
	v_lshl_add_u64 v[50:51], v[134:135], 0, s[74:75]
	v_lshl_add_u64 v[52:53], v[136:137], 0, s[74:75]
	s_addk_i32 s74, 0x180
	s_waitcnt lgkmcnt(0)
	s_barrier
	v_lshl_add_u64 v[58:59], v[144:145], 0, s[74:75]
	v_lshl_add_u64 v[60:61], v[138:139], 0, s[74:75]
	v_lshl_add_u64 v[66:67], v[146:147], 0, s[74:75]
	v_lshl_add_u64 v[68:69], v[140:141], 0, s[74:75]
	global_load_dwordx4 v[54:57], v[50:51], off offset:384
	v_lshl_add_u64 v[70:71], v[148:149], 0, s[74:75]
	global_load_dwordx4 v[50:53], v[52:53], off offset:384
	v_lshl_add_u64 v[72:73], v[142:143], 0, s[74:75]
	global_load_dwordx4 v[74:77], v[58:59], off
	s_nop 0
	global_load_dwordx4 v[58:61], v[60:61], off
	s_nop 0
	global_load_dwordx4 v[86:89], v[66:67], off
	s_nop 0
	global_load_dwordx4 v[66:69], v[68:69], off
	s_nop 0
	global_load_dwordx4 v[78:81], v[70:71], off
	v_mfma_f32_16x16x32_bf16 v[46:49], v[158:161], v[170:173], v[46:49]
	global_load_dwordx4 v[70:73], v[72:73], off
	v_mfma_f32_16x16x32_bf16 v[42:45], v[162:165], v[170:173], v[42:45]
	v_mfma_f32_16x16x32_bf16 v[38:41], v[174:177], v[170:173], v[38:41]
	v_mfma_f32_16x16x32_bf16 v[34:37], v[178:181], v[170:173], v[34:37]
	s_waitcnt lgkmcnt(9)
	v_mfma_f32_16x16x32_bf16 v[30:33], v[158:161], v[166:169], v[30:33]
	v_mfma_f32_16x16x32_bf16 v[26:29], v[162:165], v[166:169], v[26:29]
	v_mfma_f32_16x16x32_bf16 v[22:25], v[174:177], v[166:169], v[22:25]
	v_mfma_f32_16x16x32_bf16 v[18:21], v[178:181], v[166:169], v[18:21]
	s_waitcnt lgkmcnt(8)
	v_mfma_f32_16x16x32_bf16 v[14:17], v[158:161], v[182:185], v[14:17]
	v_mfma_f32_16x16x32_bf16 v[10:13], v[162:165], v[182:185], v[10:13]
	v_mfma_f32_16x16x32_bf16 v[2:5], v[174:177], v[182:185], v[2:5]
	v_mfma_f32_16x16x32_bf16 v[6:9], v[178:181], v[182:185], v[6:9]
	ds_read_b128 v[158:161], v153 offset:49152
	ds_read_b128 v[162:165], v152 offset:32768
	ds_read_b128 v[166:169], v153 offset:51200
	ds_read_b128 v[170:173], v153 offset:53248
	ds_read_b128 v[174:177], v153 offset:55296
	ds_read_b128 v[178:181], v152 offset:34816
	ds_read_b128 v[182:185], v152 offset:36864
	s_cmp_lt_u32 s6, 14
	s_waitcnt lgkmcnt(5)
; __device__ __forceinline__ f32x4 mfma16(bf16x8 a, bf16x8 b, f32x4 c) { return __builtin_amdgcn_mfma_f32_16x16x32_bf16(a, b, c, 0, 0, 0); }
; __device__ __forceinline__ void lds_barrier() { asm volatile("s_waitcnt lgkmcnt(0)\n\ts_barrier" ::: "memory"); }
; template <bool PF2>
; __device__ __forceinline__ void gemm_mainloop_t(const bf16_t* __restrict__ A, int lda, const bf16_t* __restrict__ Bt, int ldb, int K,
;                                                 bf16_t* smem, f32x4 (&acc)[4][4], const int tid) {
;     ...
;   auto compute = [&](int st) {
;     const bf16_t* as = smem + st * 2 * GSTAGE;
;     const bf16_t* bs = as + GSTAGE;
; #pragma unroll
;     for (int ks = 0; ks < 2; ++ks) {
;       bf16x8 af[4], bfr[4];
; #pragma unroll
;       for (int mi = 0; mi < 4; ++mi) af[mi] = *(const bf16x8*)(as + (wm * 64 + mi * 16 + fr) * GS + (((ks * 4 + fq) ^ (fr & 7)) * 8));
; #pragma unroll
;       for (int ni = 0; ni < 4; ++ni) bfr[ni] = *(const bf16x8*)(bs + (wn * 64 + ni * 16 + fr) * GS + (((ks * 4 + fq) ^ (fr & 7)) * 8));
; #pragma unroll
;       for (int mi = 0; mi < 4; ++mi)
; #pragma unroll
;         for (int ni = 0; ni < 4; ++ni) acc[mi][ni] = mfma16(bfr[ni], af[mi], acc[mi][ni]);
;     }
;   };
;     ...
;       sstore(1, 1);
;       lds_barrier();
;       gload(1, min(kt + 3, nk - 1));
;       __builtin_amdgcn_sched_barrier(0);
;       compute(1);
;       sstore(0, 0);
;       lds_barrier();
;     }
	v_mfma_f32_16x16x32_bf16 v[110:113], v[158:161], v[162:165], v[110:113]
	s_waitcnt lgkmcnt(4)
	v_mfma_f32_16x16x32_bf16 v[90:93], v[166:169], v[162:165], v[90:93]
	s_waitcnt lgkmcnt(3)
	v_mfma_f32_16x16x32_bf16 v[82:85], v[170:173], v[162:165], v[82:85]
	s_waitcnt lgkmcnt(2)
	v_mfma_f32_16x16x32_bf16 v[62:65], v[174:177], v[162:165], v[62:65]
	ds_read_b128 v[162:165], v152 offset:38912
	s_waitcnt lgkmcnt(2)
	v_mfma_f32_16x16x32_bf16 v[46:49], v[158:161], v[178:181], v[46:49]
	v_mfma_f32_16x16x32_bf16 v[42:45], v[166:169], v[178:181], v[42:45]
	v_mfma_f32_16x16x32_bf16 v[38:41], v[170:173], v[178:181], v[38:41]
	v_mfma_f32_16x16x32_bf16 v[34:37], v[174:177], v[178:181], v[34:37]
	ds_read_b128 v[178:181], v154 offset:32768
	s_waitcnt lgkmcnt(2)
	v_mfma_f32_16x16x32_bf16 v[30:33], v[158:161], v[182:185], v[30:33]
	v_mfma_f32_16x16x32_bf16 v[26:29], v[166:169], v[182:185], v[26:29]
	v_mfma_f32_16x16x32_bf16 v[22:25], v[170:173], v[182:185], v[22:25]
	v_mfma_f32_16x16x32_bf16 v[18:21], v[174:177], v[182:185], v[18:21]
	ds_read_b128 v[182:185], v154 offset:34816
	s_waitcnt lgkmcnt(2)
	v_mfma_f32_16x16x32_bf16 v[14:17], v[158:161], v[162:165], v[14:17]
	ds_read_b128 v[158:161], v155 offset:49152
	v_mfma_f32_16x16x32_bf16 v[10:13], v[166:169], v[162:165], v[10:13]
	ds_read_b128 v[166:169], v155 offset:51200
	v_mfma_f32_16x16x32_bf16 v[2:5], v[170:173], v[162:165], v[2:5]
	ds_read_b128 v[170:173], v155 offset:53248
	v_mfma_f32_16x16x32_bf16 v[6:9], v[174:177], v[162:165], v[6:9]
	ds_read_b128 v[174:177], v155 offset:55296
	ds_read_b128 v[162:165], v154 offset:36864
	s_waitcnt lgkmcnt(4)
	v_mfma_f32_16x16x32_bf16 v[110:113], v[158:161], v[178:181], v[110:113]
	s_waitcnt lgkmcnt(3)
	v_mfma_f32_16x16x32_bf16 v[90:93], v[166:169], v[178:181], v[90:93]
	s_waitcnt lgkmcnt(2)
	v_mfma_f32_16x16x32_bf16 v[82:85], v[170:173], v[178:181], v[82:85]
	s_waitcnt lgkmcnt(1)
	v_mfma_f32_16x16x32_bf16 v[62:65], v[174:177], v[178:181], v[62:65]
	ds_read_b128 v[178:181], v154 offset:38912
	v_mfma_f32_16x16x32_bf16 v[46:49], v[158:161], v[182:185], v[46:49]
	v_mfma_f32_16x16x32_bf16 v[42:45], v[166:169], v[182:185], v[42:45]
	v_mfma_f32_16x16x32_bf16 v[38:41], v[170:173], v[182:185], v[38:41]
	v_mfma_f32_16x16x32_bf16 v[34:37], v[174:177], v[182:185], v[34:37]
	s_waitcnt lgkmcnt(1)
	v_mfma_f32_16x16x32_bf16 v[30:33], v[158:161], v[162:165], v[30:33]
	v_mfma_f32_16x16x32_bf16 v[26:29], v[166:169], v[162:165], v[26:29]
	v_mfma_f32_16x16x32_bf16 v[22:25], v[170:173], v[162:165], v[22:25]
	v_mfma_f32_16x16x32_bf16 v[18:21], v[174:177], v[162:165], v[18:21]
	s_waitcnt vmcnt(15)
	ds_write_b128 v151, v[94:97]
	s_waitcnt vmcnt(14)
	ds_write_b128 v151, v[98:101] offset:16384
	s_waitcnt vmcnt(13)
	ds_write_b128 v151, v[102:105] offset:4096
	s_waitcnt vmcnt(12)
	ds_write_b128 v151, v[106:109] offset:20480
	s_waitcnt lgkmcnt(4)
	v_mfma_f32_16x16x32_bf16 v[14:17], v[158:161], v[178:181], v[14:17]
	s_waitcnt vmcnt(11)
	ds_write_b128 v151, v[114:117] offset:8192
	s_waitcnt vmcnt(10)
	ds_write_b128 v151, v[118:121] offset:24576
	s_waitcnt vmcnt(9)
	ds_write_b128 v151, v[122:125] offset:12288
	s_waitcnt vmcnt(8)
	ds_write_b128 v151, v[126:129] offset:28672
	s_waitcnt lgkmcnt(0)
	s_barrier
	v_mfma_f32_16x16x32_bf16 v[10:13], v[166:169], v[178:181], v[10:13]
	v_mfma_f32_16x16x32_bf16 v[2:5], v[170:173], v[178:181], v[2:5]
	v_mfma_f32_16x16x32_bf16 v[6:9], v[174:177], v[178:181], v[6:9]
	s_cbranch_scc1 .LBB0_920
; __device__ __forceinline__ void store4bf(bf16_t* p, f32x4 v) { u32x2 o; o.x = pack2(v[0], v[1]); o.y = pack2(v[2], v[3]); *(u32x2*)p = o; }
; __device__ void phase_wout(const Params& p, int l, unsigned char* smem) {
;     ...
;     const int rowb = mt * 128 + wm * 64 + fr, colb = ct * 128 + wn * 64 + fq * 4;
;     f32x4 xin[4][4];
; #pragma unroll
;     for (int mi = 0; mi < 4; ++mi)
; #pragma unroll
;       for (int ni = 0; ni < 4; ++ni) xin[mi][ni] = *(const f32x4*)((l == 0 ? p.x : p.xcur) + (size_t)(rowb + mi * 16) * 1024 + colb + ni * 16);
; #pragma unroll
;     for (int mi = 0; mi < 4; ++mi) {
;       const int row = rowb + mi * 16;
;       float s = 0.f;
; #pragma unroll
;       for (int ni = 0; ni < 4; ++ni) {
;         const f32x4 v = xin[mi][ni] + acc[mi][ni];
;         *(f32x4*)(p.xcur + (size_t)row * 1024 + colb + ni * 16) = v;
;         store4bf(p.xb + (size_t)row * 1024 + colb + ni * 16, v);
;         s += v[0] * v[0] + v[1] * v[1] + v[2] * v[2] + v[3] * v[3];
;       }
;       s = xsum_rows(s);
;       if (fq == 0) p.ssq2[row * 16 + ct * 2 + wn] = s;
	v_lshl_add_u32 v142, s3, 7, v156
	v_lshl_or_b32 v158, s2, 7, v157
	v_lshlrev_b32_e32 v0, 2, v158
	v_ashrrev_i32_e32 v143, 31, v142
	s_waitcnt vmcnt(6)
	v_lshl_add_u64 v[50:51], s[0:1], 0, v[0:1]
	v_lshlrev_b64 v[148:149], 12, v[142:143]
	v_lshl_add_u64 v[52:53], v[50:51], 0, v[148:149]
	global_load_dwordx4 v[144:147], v[52:53], off
	global_load_dwordx4 v[122:125], v[52:53], off offset:64
	global_load_dwordx4 v[118:121], v[52:53], off offset:128
	global_load_dwordx4 v[114:117], v[52:53], off offset:192
	v_or_b32_e32 v138, 16, v142
	v_ashrrev_i32_e32 v139, 31, v138
	v_or_b32_e32 v128, 32, v142
	v_or_b32_e32 v126, 48, v142
	v_lshlrev_b64 v[140:141], 12, v[138:139]
	v_ashrrev_i32_e32 v129, 31, v128
	v_ashrrev_i32_e32 v127, 31, v126
	v_lshl_add_u64 v[52:53], v[50:51], 0, v[140:141]
	v_lshlrev_b64 v[136:137], 12, v[128:129]
	v_lshlrev_b64 v[134:135], 12, v[126:127]
	global_load_dwordx4 v[106:109], v[52:53], off
	global_load_dwordx4 v[102:105], v[52:53], off offset:64
	global_load_dwordx4 v[98:101], v[52:53], off offset:128
	global_load_dwordx4 v[94:97], v[52:53], off offset:192
	v_lshl_add_u64 v[52:53], v[50:51], 0, v[136:137]
	v_lshl_add_u64 v[50:51], v[50:51], 0, v[134:135]
	global_load_dwordx4 v[86:89], v[52:53], off
	global_load_dwordx4 v[78:81], v[52:53], off offset:64
	global_load_dwordx4 v[74:77], v[52:53], off offset:128
	global_load_dwordx4 v[66:69], v[52:53], off offset:192
	global_load_dwordx4 v[70:73], v[50:51], off
	global_load_dwordx4 v[58:61], v[50:51], off offset:64
	global_load_dwordx4 v[54:57], v[50:51], off offset:128
	s_nop 0
	global_load_dwordx4 v[50:53], v[50:51], off offset:192
	v_readlane_b32 s12, v252, 25
	v_readlane_b32 s13, v252, 26
	v_readlane_b32 s14, v252, 27
	v_readlane_b32 s15, v252, 28
	s_lshl_b32 s6, s2, 1
	v_readlane_b32 s16, v252, 29
	v_readlane_b32 s17, v252, 30
	v_readlane_b32 s18, v252, 31
	v_readlane_b32 s19, v252, 32
	v_readlane_b32 s20, v252, 33
	v_readlane_b32 s21, v252, 34
	v_readlane_b32 s22, v252, 35
	v_readlane_b32 s23, v252, 36
	v_readlane_b32 s24, v252, 37
	v_readlane_b32 s25, v252, 38
	v_readlane_b32 s26, v252, 39
	v_readlane_b32 s27, v252, 40
	s_waitcnt vmcnt(15)
	v_pk_add_f32 v[144:145], v[110:111], v[144:145]
	v_lshl_add_u64 v[110:111], s[12:13], 0, v[148:149]
	v_pk_add_f32 v[146:147], v[112:113], v[146:147]
	v_lshl_add_u64 v[112:113], v[110:111], 0, v[0:1]
	v_lshlrev_b64 v[110:111], 11, v[142:143]
	v_lshl_add_u64 v[148:149], s[14:15], 0, v[110:111]
	v_lshlrev_b32_e32 v110, 1, v158
	v_mov_b32_e32 v111, v1
	v_lshl_add_u64 v[148:149], v[148:149], 0, v[110:111]
	s_waitcnt vmcnt(14)
	v_pk_add_f32 v[92:93], v[92:93], v[124:125]
	v_pk_add_f32 v[90:91], v[90:91], v[122:123]
	global_store_dwordx4 v[112:113], v[144:147], off
	v_cvt_pk_bf16_f32 v158, v144, v145
	v_cvt_pk_bf16_f32 v159, v146, v147
	global_store_dwordx2 v[148:149], v[158:159], off
	v_mul_f32_e32 v143, v145, v145
	global_store_dwordx4 v[112:113], v[90:93], off offset:64
	v_cvt_pk_bf16_f32 v122, v90, v91
	v_fmac_f32_e32 v143, v144, v144
	v_fmac_f32_e32 v143, v146, v146
	v_mul_f32_e32 v91, v91, v91
	v_fmac_f32_e32 v91, v90, v90
	v_fmac_f32_e32 v91, v92, v92
	s_waitcnt vmcnt(16)
	v_pk_add_f32 v[84:85], v[84:85], v[120:121]
	v_pk_add_f32 v[82:83], v[82:83], v[118:119]
	v_fmac_f32_e32 v143, v147, v147
	v_cvt_pk_bf16_f32 v123, v92, v93
	global_store_dwordx2 v[148:149], v[122:123], off offset:32
	v_fmac_f32_e32 v91, v93, v93
	global_store_dwordx4 v[112:113], v[82:85], off offset:128
	v_cvt_pk_bf16_f32 v90, v82, v83
	s_waitcnt vmcnt(17)
	v_pk_add_f32 v[64:65], v[64:65], v[116:117]
	v_pk_add_f32 v[62:63], v[62:63], v[114:115]
	v_mul_f32_e32 v83, v83, v83
	v_add_f32_e32 v92, v143, v91
	v_cvt_pk_bf16_f32 v91, v84, v85
	global_store_dwordx2 v[148:149], v[90:91], off offset:64
	v_fmac_f32_e32 v83, v82, v82
	global_store_dwordx4 v[112:113], v[62:65], off offset:192
	v_cvt_pk_bf16_f32 v82, v62, v63
	v_fmac_f32_e32 v83, v84, v84
	v_fmac_f32_e32 v83, v85, v85
	v_mul_f32_e32 v63, v63, v63
	v_fmac_f32_e32 v63, v62, v62
	v_fmac_f32_e32 v63, v64, v64
	v_add_f32_e32 v84, v92, v83
	v_fmac_f32_e32 v63, v65, v65
	v_add_f32_e32 v62, v84, v63
	v_mov_b32_e32 v63, v62
	s_nop 1
	v_permlane16_swap_b32_e32 v62, v63
	v_add_f32_e32 v62, v62, v63
	v_mov_b32_e32 v63, v62
	s_nop 1
	v_permlane32_swap_b32_e32 v62, v63
	v_cvt_pk_bf16_f32 v83, v64, v65
	global_store_dwordx2 v[148:149], v[82:83], off offset:96
	s_and_saveexec_b64 s[2:3], vcc
	s_cbranch_execz .LBB0_923
	v_add_f32_e32 v64, v62, v63
	v_lshlrev_b32_e32 v62, 4, v142
	v_or3_b32 v62, v62, s6, v150
	v_readlane_b32 s12, v253, 61
	v_ashrrev_i32_e32 v63, 31, v62
	v_readlane_b32 s16, v254, 1
	v_readlane_b32 s17, v254, 2
	v_readlane_b32 s13, v253, 62
	v_readlane_b32 s14, v253, 63
	v_lshl_add_u64 v[62:63], v[62:63], 2, s[16:17]
	v_readlane_b32 s15, v254, 0
	v_readlane_b32 s18, v254, 3
	v_readlane_b32 s19, v254, 4
	v_readlane_b32 s20, v254, 5
	v_readlane_b32 s21, v254, 6
	v_readlane_b32 s22, v254, 7
	v_readlane_b32 s23, v254, 8
	v_readlane_b32 s24, v254, 9
	v_readlane_b32 s25, v254, 10
	v_readlane_b32 s26, v254, 11
	v_readlane_b32 s27, v254, 12
	global_store_dword v[62:63], v64, off

; __device__ __forceinline__ void lds_barrier() { asm volatile("s_waitcnt lgkmcnt(0)\n\ts_barrier" ::: "memory"); }
; template <bool PF2>
; __device__ __forceinline__ void gemm_mainloop_t(const bf16_t* __restrict__ A, int lda, const bf16_t* __restrict__ Bt, int ldb, int K,
;                                                 bf16_t* smem, f32x4 (&acc)[4][4], const int tid) {
;     ...
;   if (PF2) {
;     gload(0, 0);
;     gload(1, 1);
;     sstore(0, 0);
;     lds_barrier();
;     for (int kt = 0; kt < nk; kt += 2) {
;       gload(0, min(kt + 2, nk - 1));
;       __builtin_amdgcn_sched_barrier(0);
;       compute(0);
;       sstore(1, 1);
;       lds_barrier();
;       gload(1, min(kt + 3, nk - 1));
;       __builtin_amdgcn_sched_barrier(0);
;       compute(1);
;       sstore(0, 0);
;       lds_barrier();
;     }
.LBB0_976:
	s_add_i32 s4, s3, 4
	s_min_u32 s4, s4, 15
	s_lshl_b32 s74, s4, 7
	v_lshl_add_u64 v[98:99], v[134:135], 0, s[74:75]
	v_lshl_add_u64 v[102:103], v[136:137], 0, s[74:75]
	v_lshl_add_u64 v[106:107], v[144:145], 0, s[74:75]
	v_lshl_add_u64 v[110:111], v[138:139], 0, s[74:75]
	v_lshl_add_u64 v[114:115], v[146:147], 0, s[74:75]
	v_lshl_add_u64 v[118:119], v[140:141], 0, s[74:75]
	v_lshl_add_u64 v[122:123], v[148:149], 0, s[74:75]
	v_lshl_add_u64 v[126:127], v[142:143], 0, s[74:75]
	global_load_dwordx4 v[98:101], v[98:99], off
	s_add_i32 s3, s3, 2
	global_load_dwordx4 v[102:105], v[102:103], off
	s_nop 0
	global_load_dwordx4 v[106:109], v[106:107], off
	s_nop 0
	global_load_dwordx4 v[110:113], v[110:111], off
	s_nop 0
	global_load_dwordx4 v[114:117], v[114:115], off
	s_nop 0
	global_load_dwordx4 v[118:121], v[118:119], off
	s_nop 0
	global_load_dwordx4 v[122:125], v[122:123], off
	s_nop 0
	global_load_dwordx4 v[126:129], v[126:127], off
	ds_read_b128 v[158:161], v152 offset:16384
	ds_read_b128 v[162:165], v152 offset:18432
	ds_read_b128 v[166:169], v151
	ds_read_b128 v[170:173], v151 offset:2048
	ds_read_b128 v[174:177], v152 offset:20480
	ds_read_b128 v[178:181], v152 offset:22528
	s_min_u32 s4, s3, 12
	s_waitcnt lgkmcnt(3)
	v_mfma_f32_16x16x32_bf16 v[62:65], v[158:161], v[166:169], v[62:65]
	s_lshl_b32 s74, s4, 7
	v_mfma_f32_16x16x32_bf16 v[58:61], v[162:165], v[166:169], v[58:61]
	s_waitcnt lgkmcnt(1)
	v_mfma_f32_16x16x32_bf16 v[54:57], v[174:177], v[166:169], v[54:57]
	s_waitcnt lgkmcnt(0)
	v_mfma_f32_16x16x32_bf16 v[50:53], v[178:181], v[166:169], v[50:53]
	v_mfma_f32_16x16x32_bf16 v[46:49], v[158:161], v[170:173], v[46:49]
	v_mfma_f32_16x16x32_bf16 v[42:45], v[162:165], v[170:173], v[42:45]
	v_mfma_f32_16x16x32_bf16 v[38:41], v[174:177], v[170:173], v[38:41]
	v_mfma_f32_16x16x32_bf16 v[34:37], v[178:181], v[170:173], v[34:37]
	ds_read_b128 v[166:169], v151 offset:4096
	ds_read_b128 v[170:173], v151 offset:6144
	s_waitcnt lgkmcnt(1)
	v_mfma_f32_16x16x32_bf16 v[30:33], v[158:161], v[166:169], v[30:33]
	v_mfma_f32_16x16x32_bf16 v[26:29], v[162:165], v[166:169], v[26:29]
	v_mfma_f32_16x16x32_bf16 v[22:25], v[174:177], v[166:169], v[22:25]
	v_mfma_f32_16x16x32_bf16 v[18:21], v[178:181], v[166:169], v[18:21]
	s_waitcnt lgkmcnt(0)
	v_mfma_f32_16x16x32_bf16 v[14:17], v[158:161], v[170:173], v[14:17]
	v_mfma_f32_16x16x32_bf16 v[6:9], v[162:165], v[170:173], v[6:9]
	ds_read_b128 v[158:161], v154 offset:16384
	ds_read_b128 v[162:165], v154 offset:18432
	v_mfma_f32_16x16x32_bf16 v[2:5], v[174:177], v[170:173], v[2:5]
	v_mfma_f32_16x16x32_bf16 v[10:13], v[178:181], v[170:173], v[10:13]
	ds_read_b128 v[166:169], v153
	ds_read_b128 v[170:173], v153 offset:2048
	ds_read_b128 v[174:177], v154 offset:20480
	ds_read_b128 v[178:181], v154 offset:22528
	s_waitcnt lgkmcnt(3)
	v_mfma_f32_16x16x32_bf16 v[62:65], v[158:161], v[166:169], v[62:65]
	v_mfma_f32_16x16x32_bf16 v[58:61], v[162:165], v[166:169], v[58:61]
	s_waitcnt lgkmcnt(1)
	v_mfma_f32_16x16x32_bf16 v[54:57], v[174:177], v[166:169], v[54:57]
	s_waitcnt lgkmcnt(0)
	v_mfma_f32_16x16x32_bf16 v[50:53], v[178:181], v[166:169], v[50:53]
	ds_read_b128 v[166:169], v153 offset:4096
	ds_read_b128 v[182:185], v153 offset:6144
	s_waitcnt vmcnt(15)
	ds_write_b128 v150, v[70:73] offset:32768
	s_waitcnt vmcnt(14)
	ds_write_b128 v150, v[66:69] offset:49152
	s_waitcnt vmcnt(13)
	ds_write_b128 v150, v[86:89] offset:36864
	s_waitcnt vmcnt(12)
	ds_write_b128 v150, v[74:77] offset:53248
	s_waitcnt vmcnt(11)
	ds_write_b128 v150, v[94:97] offset:40960
	s_waitcnt vmcnt(10)
	ds_write_b128 v150, v[78:81] offset:57344
	s_waitcnt vmcnt(9)
	ds_write_b128 v150, v[90:93] offset:45056
	s_waitcnt vmcnt(8)
	ds_write_b128 v150, v[82:85] offset:61440
	v_lshl_add_u64 v[66:67], v[134:135], 0, s[74:75]
	v_lshl_add_u64 v[68:69], v[136:137], 0, s[74:75]
	s_addk_i32 s74, 0x180
	s_waitcnt lgkmcnt(0)
	s_barrier
	v_lshl_add_u64 v[74:75], v[144:145], 0, s[74:75]
	v_lshl_add_u64 v[76:77], v[138:139], 0, s[74:75]
	v_lshl_add_u64 v[78:79], v[146:147], 0, s[74:75]
	v_lshl_add_u64 v[80:81], v[140:141], 0, s[74:75]
	global_load_dwordx4 v[70:73], v[66:67], off offset:384
	v_lshl_add_u64 v[82:83], v[148:149], 0, s[74:75]
	global_load_dwordx4 v[66:69], v[68:69], off offset:384
	v_lshl_add_u64 v[84:85], v[142:143], 0, s[74:75]
	global_load_dwordx4 v[86:89], v[74:75], off
	s_nop 0
	global_load_dwordx4 v[74:77], v[76:77], off
	s_nop 0
	global_load_dwordx4 v[94:97], v[78:79], off
	s_nop 0
	global_load_dwordx4 v[78:81], v[80:81], off
	s_nop 0
	global_load_dwordx4 v[90:93], v[82:83], off
	v_mfma_f32_16x16x32_bf16 v[46:49], v[158:161], v[170:173], v[46:49]
	global_load_dwordx4 v[82:85], v[84:85], off
	v_mfma_f32_16x16x32_bf16 v[42:45], v[162:165], v[170:173], v[42:45]
	v_mfma_f32_16x16x32_bf16 v[38:41], v[174:177], v[170:173], v[38:41]
	v_mfma_f32_16x16x32_bf16 v[34:37], v[178:181], v[170:173], v[34:37]
	s_waitcnt lgkmcnt(9)
	v_mfma_f32_16x16x32_bf16 v[30:33], v[158:161], v[166:169], v[30:33]
	v_mfma_f32_16x16x32_bf16 v[26:29], v[162:165], v[166:169], v[26:29]
	v_mfma_f32_16x16x32_bf16 v[22:25], v[174:177], v[166:169], v[22:25]
	v_mfma_f32_16x16x32_bf16 v[18:21], v[178:181], v[166:169], v[18:21]
	s_waitcnt lgkmcnt(8)
	v_mfma_f32_16x16x32_bf16 v[14:17], v[158:161], v[182:185], v[14:17]
	v_mfma_f32_16x16x32_bf16 v[6:9], v[162:165], v[182:185], v[6:9]
	v_mfma_f32_16x16x32_bf16 v[2:5], v[174:177], v[182:185], v[2:5]
	v_mfma_f32_16x16x32_bf16 v[10:13], v[178:181], v[182:185], v[10:13]
	ds_read_b128 v[158:161], v152 offset:49152
	ds_read_b128 v[162:165], v151 offset:32768
	ds_read_b128 v[166:169], v152 offset:51200
	ds_read_b128 v[170:173], v152 offset:53248
	ds_read_b128 v[174:177], v152 offset:55296
	ds_read_b128 v[178:181], v151 offset:34816
	ds_read_b128 v[182:185], v151 offset:36864
	s_cmp_lt_u32 s3, 14
	s_waitcnt lgkmcnt(5)
; __device__ __forceinline__ f32x4 mfma16(bf16x8 a, bf16x8 b, f32x4 c) { return __builtin_amdgcn_mfma_f32_16x16x32_bf16(a, b, c, 0, 0, 0); }
; template <bool PF2>
; __device__ __forceinline__ void gemm_mainloop_t(const bf16_t* __restrict__ A, int lda, const bf16_t* __restrict__ Bt, int ldb, int K,
;                                                 bf16_t* smem, f32x4 (&acc)[4][4], const int tid) {
;     ...
;   auto compute = [&](int st) {
;     const bf16_t* as = smem + st * 2 * GSTAGE;
;     const bf16_t* bs = as + GSTAGE;
; #pragma unroll
;     for (int ks = 0; ks < 2; ++ks) {
;       bf16x8 af[4], bfr[4];
; #pragma unroll
;       for (int mi = 0; mi < 4; ++mi) af[mi] = *(const bf16x8*)(as + (wm * 64 + mi * 16 + fr) * GS + (((ks * 4 + fq) ^ (fr & 7)) * 8));
; #pragma unroll
;       for (int ni = 0; ni < 4; ++ni) bfr[ni] = *(const bf16x8*)(bs + (wn * 64 + ni * 16 + fr) * GS + (((ks * 4 + fq) ^ (fr & 7)) * 8));
; #pragma unroll
;       for (int mi = 0; mi < 4; ++mi)
; #pragma unroll
;         for (int ni = 0; ni < 4; ++ni) acc[mi][ni] = mfma16(bfr[ni], af[mi], acc[mi][ni]);
;     }
;   };
; __device__ void phase_pq(const Params& p, int l, unsigned char* smem) {
;     ...
;     f32x4 sq[4][4];
; #pragma unroll
;     for (int mi = 0; mi < 4; ++mi)
; #pragma unroll
;       for (int i = 0; i < 4; ++i) sq[mi][i] = *(const f32x4*)(p.ssq2 + (rowb + mi * 16) * 16 + i * 4);
; #pragma unroll
;     for (int mi = 0; mi < 4; ++mi) {
;       const int row = rowb + mi * 16;
;       float s = 0.f;
; #pragma unroll
;       for (int i = 0; i < 4; ++i) s += sq[mi][i][0] + sq[mi][i][1] + sq[mi][i][2] + sq[mi][i][3];
;       const float rstd = rsqrtf(s * (1.f / 1024.f) + 1e-6f);
	v_mfma_f32_16x16x32_bf16 v[62:65], v[158:161], v[162:165], v[62:65]
	s_waitcnt lgkmcnt(4)
	v_mfma_f32_16x16x32_bf16 v[58:61], v[166:169], v[162:165], v[58:61]
	s_waitcnt lgkmcnt(3)
	v_mfma_f32_16x16x32_bf16 v[54:57], v[170:173], v[162:165], v[54:57]
	s_waitcnt lgkmcnt(2)
	v_mfma_f32_16x16x32_bf16 v[50:53], v[174:177], v[162:165], v[50:53]
	ds_read_b128 v[162:165], v151 offset:38912
	s_waitcnt lgkmcnt(2)
	v_mfma_f32_16x16x32_bf16 v[46:49], v[158:161], v[178:181], v[46:49]
	v_mfma_f32_16x16x32_bf16 v[42:45], v[166:169], v[178:181], v[42:45]
	v_mfma_f32_16x16x32_bf16 v[38:41], v[170:173], v[178:181], v[38:41]
	v_mfma_f32_16x16x32_bf16 v[34:37], v[174:177], v[178:181], v[34:37]
	ds_read_b128 v[178:181], v153 offset:32768
	s_waitcnt lgkmcnt(2)
	v_mfma_f32_16x16x32_bf16 v[30:33], v[158:161], v[182:185], v[30:33]
	v_mfma_f32_16x16x32_bf16 v[26:29], v[166:169], v[182:185], v[26:29]
	v_mfma_f32_16x16x32_bf16 v[22:25], v[170:173], v[182:185], v[22:25]
	v_mfma_f32_16x16x32_bf16 v[18:21], v[174:177], v[182:185], v[18:21]
	ds_read_b128 v[182:185], v153 offset:34816
	s_waitcnt lgkmcnt(2)
	v_mfma_f32_16x16x32_bf16 v[14:17], v[158:161], v[162:165], v[14:17]
	ds_read_b128 v[158:161], v154 offset:49152
	v_mfma_f32_16x16x32_bf16 v[6:9], v[166:169], v[162:165], v[6:9]
	ds_read_b128 v[166:169], v154 offset:51200
	v_mfma_f32_16x16x32_bf16 v[2:5], v[170:173], v[162:165], v[2:5]
	ds_read_b128 v[170:173], v154 offset:53248
	v_mfma_f32_16x16x32_bf16 v[10:13], v[174:177], v[162:165], v[10:13]
	ds_read_b128 v[174:177], v154 offset:55296
	ds_read_b128 v[162:165], v153 offset:36864
	s_waitcnt lgkmcnt(4)
	v_mfma_f32_16x16x32_bf16 v[62:65], v[158:161], v[178:181], v[62:65]
	s_waitcnt lgkmcnt(3)
	v_mfma_f32_16x16x32_bf16 v[58:61], v[166:169], v[178:181], v[58:61]
	s_waitcnt lgkmcnt(2)
	v_mfma_f32_16x16x32_bf16 v[54:57], v[170:173], v[178:181], v[54:57]
	s_waitcnt lgkmcnt(1)
	v_mfma_f32_16x16x32_bf16 v[50:53], v[174:177], v[178:181], v[50:53]
	ds_read_b128 v[178:181], v153 offset:38912
	v_mfma_f32_16x16x32_bf16 v[46:49], v[158:161], v[182:185], v[46:49]
	v_mfma_f32_16x16x32_bf16 v[42:45], v[166:169], v[182:185], v[42:45]
	v_mfma_f32_16x16x32_bf16 v[38:41], v[170:173], v[182:185], v[38:41]
	v_mfma_f32_16x16x32_bf16 v[34:37], v[174:177], v[182:185], v[34:37]
	s_waitcnt lgkmcnt(1)
	v_mfma_f32_16x16x32_bf16 v[30:33], v[158:161], v[162:165], v[30:33]
	v_mfma_f32_16x16x32_bf16 v[26:29], v[166:169], v[162:165], v[26:29]
	v_mfma_f32_16x16x32_bf16 v[22:25], v[170:173], v[162:165], v[22:25]
	v_mfma_f32_16x16x32_bf16 v[18:21], v[174:177], v[162:165], v[18:21]
	s_waitcnt vmcnt(15)
	ds_write_b128 v150, v[98:101]
	s_waitcnt vmcnt(14)
	ds_write_b128 v150, v[102:105] offset:16384
	s_waitcnt vmcnt(13)
	ds_write_b128 v150, v[106:109] offset:4096
	s_waitcnt vmcnt(12)
	ds_write_b128 v150, v[110:113] offset:20480
	s_waitcnt lgkmcnt(4)
	v_mfma_f32_16x16x32_bf16 v[14:17], v[158:161], v[178:181], v[14:17]
	s_waitcnt vmcnt(11)
	ds_write_b128 v150, v[114:117] offset:8192
	s_waitcnt vmcnt(10)
	ds_write_b128 v150, v[118:121] offset:24576
	s_waitcnt vmcnt(9)
	ds_write_b128 v150, v[122:125] offset:12288
	s_waitcnt vmcnt(8)
	ds_write_b128 v150, v[126:129] offset:28672
	s_waitcnt lgkmcnt(0)
	s_barrier
	v_mfma_f32_16x16x32_bf16 v[6:9], v[166:169], v[178:181], v[6:9]
	v_mfma_f32_16x16x32_bf16 v[2:5], v[170:173], v[178:181], v[2:5]
	v_mfma_f32_16x16x32_bf16 v[10:13], v[174:177], v[178:181], v[10:13]
	s_cbranch_scc1 .LBB0_976
	s_waitcnt vmcnt(1)
	v_lshl_add_u32 v90, s2, 7, v155
	v_lshlrev_b32_e32 v66, 4, v90
	v_readlane_b32 s8, v253, 61
	v_ashrrev_i32_e32 v67, 31, v66
	v_readlane_b32 s12, v254, 1
	v_readlane_b32 s13, v254, 2
	s_mov_b32 s2, 0x358637bd
	v_ashrrev_i32_e32 v91, 31, v90
	v_lshl_add_u64 v[94:95], v[66:67], 2, s[12:13]
	global_load_dwordx4 v[98:101], v[94:95], off
	global_load_dwordx4 v[102:105], v[94:95], off offset:16
	global_load_dwordx4 v[106:109], v[94:95], off offset:32
	global_load_dwordx4 v[110:113], v[94:95], off offset:48
	global_load_dwordx4 v[114:117], v[94:95], off offset:1024
	global_load_dwordx4 v[118:121], v[94:95], off offset:1040
	global_load_dwordx4 v[122:125], v[94:95], off offset:1056
	global_load_dwordx4 v[126:129], v[94:95], off offset:1072
	v_readlane_b32 s14, v254, 3
	v_readlane_b32 s15, v254, 4
	v_mov_b64_e32 v[92:93], s[2:3]
	v_lshlrev_b64 v[66:67], 11, v[90:91]
	s_mov_b32 s2, 0x3a800000
	v_lshl_add_u64 v[134:135], s[14:15], 0, v[66:67]
	global_load_dwordx4 v[78:81], v[94:95], off offset:2080
	global_load_dwordx4 v[74:77], v[94:95], off offset:2096
	global_load_dwordx4 v[86:89], v[94:95], off offset:2048
	global_load_dwordx4 v[82:85], v[94:95], off offset:2064
	global_load_dwordx4 v[70:73], v[94:95], off offset:3072
	global_load_dwordx4 v[66:69], v[94:95], off offset:3088
	v_lshl_or_b32 v0, s1, 8, v156
	v_or_b32_e32 v96, 16, v90
	s_add_i32 s0, s0, 1
	s_mul_i32 s1, s0, s43
	v_readlane_b32 s9, v253, 62
	v_readlane_b32 s10, v253, 63
	v_readlane_b32 s11, v254, 0
	v_readlane_b32 s16, v254, 5
	v_readlane_b32 s17, v254, 6
	v_readlane_b32 s18, v254, 7
	v_readlane_b32 s19, v254, 8
	v_readlane_b32 s20, v254, 9
	v_readlane_b32 s21, v254, 10
	v_readlane_b32 s22, v254, 11
	v_readlane_b32 s23, v254, 12
	s_waitcnt vmcnt(13)
	v_mov_b32_e32 v136, v98
	s_waitcnt vmcnt(12)
	v_mov_b32_e32 v137, v102
	v_mov_b32_e32 v102, v99
	v_mov_b32_e32 v98, v100
	v_mov_b32_e32 v99, v104
	v_mov_b32_e32 v104, v101
	s_waitcnt vmcnt(11)
	v_mov_b32_e32 v100, v106
	s_waitcnt vmcnt(10)
	v_mov_b32_e32 v101, v110
	v_mov_b32_e32 v110, v107
	v_mov_b32_e32 v106, v108
	v_mov_b32_e32 v107, v112
	v_mov_b32_e32 v112, v109
	s_waitcnt vmcnt(9)
	v_mov_b32_e32 v108, v114
	s_waitcnt vmcnt(8)
; __device__ __forceinline__ void store4bf(bf16_t* p, f32x4 v) { u32x2 o; o.x = pack2(v[0], v[1]); o.y = pack2(v[2], v[3]); *(u32x2*)p = o; }
; __device__ void phase_pq(const Params& p, int l, unsigned char* smem) {
;     ...
;     for (int mi = 0; mi < 4; ++mi) {
;       const int row = rowb + mi * 16;
;       float s = 0.f;
; #pragma unroll
;       for (int i = 0; i < 4; ++i) s += sq[mi][i][0] + sq[mi][i][1] + sq[mi][i][2] + sq[mi][i][3];
;       const float rstd = rsqrtf(s * (1.f / 1024.f) + 1e-6f);
; #pragma unroll
;       for (int ni = 0; ni < 4; ++ni) store4bf(p.pq + (size_t)row * 1024 + colb + ni * 16, acc[mi][ni] * rstd);
;     }
	v_mov_b32_e32 v109, v118
	v_mov_b32_e32 v118, v115
	v_mov_b32_e32 v114, v116
	v_mov_b32_e32 v115, v120
	v_mov_b32_e32 v120, v117
	s_waitcnt vmcnt(7)
	v_mov_b32_e32 v116, v122
	s_waitcnt vmcnt(6)
	v_mov_b32_e32 v117, v126
	v_mov_b32_e32 v126, v123
	v_pk_add_f32 v[102:103], v[136:137], v[102:103]
	v_pk_add_f32 v[108:109], v[108:109], v[118:119]
	v_mov_b32_e32 v122, v124
	v_mov_b32_e32 v123, v128
	v_pk_add_f32 v[100:101], v[100:101], v[110:111]
	v_pk_add_f32 v[110:111], v[116:117], v[126:127]
	v_pk_add_f32 v[98:99], v[98:99], v[102:103]
	v_pk_add_f32 v[102:103], v[114:115], v[108:109]
	v_mov_b32_e32 v128, v125
	v_pk_add_f32 v[100:101], v[106:107], v[100:101]
	v_pk_add_f32 v[106:107], v[122:123], v[110:111]
	v_pk_add_f32 v[98:99], v[104:105], v[98:99]
	v_pk_add_f32 v[102:103], v[120:121], v[102:103]
	v_pk_add_f32 v[100:101], v[112:113], v[100:101]
	v_pk_add_f32 v[104:105], v[128:129], v[106:107]
	v_mov_b32_e32 v106, v102
	v_mov_b32_e32 v107, v98
	v_mov_b32_e32 v98, v103
	v_mov_b32_e32 v102, v104
	v_mov_b32_e32 v103, v100
	v_mov_b32_e32 v100, v105
	v_pk_add_f32 v[104:105], v[106:107], 0 op_sel_hi:[1,0]
	s_nop 0
	v_pk_add_f32 v[98:99], v[104:105], v[98:99]
	s_nop 0
	v_pk_add_f32 v[98:99], v[98:99], v[102:103]
	s_nop 0
	v_pk_add_f32 v[98:99], v[98:99], v[100:101]
	s_nop 0
	v_pk_fma_f32 v[98:99], v[98:99], s[2:3], v[92:93] op_sel_hi:[1,0,0]
	s_nop 0
	v_mul_f32_e32 v91, 0x4b800000, v99
	v_mul_f32_e32 v97, 0x4b800000, v98
	v_cmp_gt_f32_e64 s[4:5], s6, v99
	v_cmp_gt_f32_e32 vcc, s6, v98
	s_nop 0
	v_cndmask_b32_e64 v91, v99, v91, s[4:5]
	v_cndmask_b32_e32 v97, v98, v97, vcc
	global_load_dwordx4 v[98:101], v[94:95], off offset:3104
	global_load_dwordx4 v[102:105], v[94:95], off offset:3120
	v_rsq_f32_e32 v91, v91
	v_rsq_f32_e32 v97, v97
	v_lshl_add_u64 v[94:95], v[134:135], 0, v[0:1]
	v_mul_f32_e32 v106, 0x45800000, v91
	v_mul_f32_e32 v107, 0x45800000, v97
	v_cndmask_b32_e64 v106, v91, v106, s[4:5]
	v_pk_mul_f32 v[62:63], v[62:63], v[106:107] op_sel_hi:[1,0]
	v_pk_mul_f32 v[50:51], v[50:51], v[106:107] op_sel_hi:[1,0]
	v_pk_mul_f32 v[64:65], v[64:65], v[106:107] op_sel_hi:[1,0]
	v_pk_mul_f32 v[58:59], v[58:59], v[106:107] op_sel_hi:[1,0]
	v_pk_mul_f32 v[54:55], v[54:55], v[106:107] op_sel_hi:[1,0]
	v_cvt_pk_bf16_f32 v62, v62, v63
	v_cvt_pk_bf16_f32 v63, v64, v65
	v_cvt_pk_bf16_f32 v50, v50, v51
	v_pk_mul_f32 v[60:61], v[60:61], v[106:107] op_sel_hi:[1,0]
	v_pk_mul_f32 v[56:57], v[56:57], v[106:107] op_sel_hi:[1,0]
	v_pk_mul_f32 v[52:53], v[52:53], v[106:107] op_sel_hi:[1,0]
	v_cvt_pk_bf16_f32 v58, v58, v59
	v_cvt_pk_bf16_f32 v59, v60, v61
	v_cvt_pk_bf16_f32 v54, v54, v55
	v_cvt_pk_bf16_f32 v55, v56, v57
	s_nop 0
	v_cvt_pk_bf16_f32 v51, v52, v53
	global_store_dwordx2 v[94:95], v[62:63], off
	global_store_dwordx2 v[94:95], v[58:59], off offset:32
	global_store_dwordx2 v[94:95], v[54:55], off offset:64
	global_store_dwordx2 v[94:95], v[50:51], off offset:96
	v_cndmask_b32_e32 v50, v97, v107, vcc
	v_ashrrev_i32_e32 v97, 31, v96
	v_lshlrev_b64 v[52:53], 11, v[96:97]
	v_lshl_add_u64 v[52:53], s[14:15], 0, v[52:53]
	v_pk_mul_f32 v[34:35], v[34:35], v[50:51] op_sel_hi:[1,0]
	v_lshl_add_u64 v[52:53], v[52:53], 0, v[0:1]
	v_pk_mul_f32 v[42:43], v[42:43], v[50:51] op_sel_hi:[1,0]
	v_pk_mul_f32 v[40:41], v[40:41], v[50:51] op_sel_hi:[1,0]
	v_pk_mul_f32 v[38:39], v[38:39], v[50:51] op_sel_hi:[1,0]
	v_pk_mul_f32 v[36:37], v[36:37], v[50:51] op_sel_hi:[1,0]
	v_cvt_pk_bf16_f32 v34, v34, v35
	v_pk_mul_f32 v[44:45], v[44:45], v[50:51] op_sel_hi:[1,0]
	v_cvt_pk_bf16_f32 v35, v36, v37
	v_cvt_pk_bf16_f32 v42, v42, v43
	v_cvt_pk_bf16_f32 v38, v38, v39
	v_cvt_pk_bf16_f32 v39, v40, v41
	global_store_dwordx2 v[52:53], v[34:35], off offset:96
	v_cvt_pk_bf16_f32 v43, v44, v45
	s_waitcnt vmcnt(10)
	v_mov_b32_e32 v34, v86
	s_waitcnt vmcnt(9)
	v_mov_b32_e32 v35, v82
	v_mov_b32_e32 v82, v87
	s_waitcnt vmcnt(8)
	v_mov_b32_e32 v40, v70
	s_waitcnt vmcnt(7)
; __device__ __forceinline__ void store4bf(bf16_t* p, f32x4 v) { u32x2 o; o.x = pack2(v[0], v[1]); o.y = pack2(v[2], v[3]); *(u32x2*)p = o; }
; __device__ void phase_pq(const Params& p, int l, unsigned char* smem) {
;     ...
;   for (int it = 0; xcd_tile(it, 128, 8, mt, ct); ++it) {
;     ...
;     for (int mi = 0; mi < 4; ++mi) {
;       const int row = rowb + mi * 16;
;       float s = 0.f;
; #pragma unroll
;       for (int i = 0; i < 4; ++i) s += sq[mi][i][0] + sq[mi][i][1] + sq[mi][i][2] + sq[mi][i][3];
;       const float rstd = rsqrtf(s * (1.f / 1024.f) + 1e-6f);
; #pragma unroll
;       for (int ni = 0; ni < 4; ++ni) store4bf(p.pq + (size_t)row * 1024 + colb + ni * 16, acc[mi][ni] * rstd);
;     }
	v_mov_b32_e32 v41, v66
	v_mov_b32_e32 v66, v71
	global_store_dwordx2 v[52:53], v[42:43], off offset:32
	v_pk_add_f32 v[34:35], v[34:35], v[82:83]
	v_mov_b32_e32 v36, v88
	v_mov_b32_e32 v37, v84
	v_pk_add_f32 v[40:41], v[40:41], v[66:67]
	v_mov_b32_e32 v42, v72
	v_mov_b32_e32 v43, v68
	v_pk_add_f32 v[34:35], v[36:37], v[34:35]
	v_mov_b32_e32 v84, v89
	v_mov_b32_e32 v36, v78
	v_mov_b32_e32 v37, v74
	v_mov_b32_e32 v74, v79
	v_pk_add_f32 v[40:41], v[42:43], v[40:41]
	v_mov_b32_e32 v68, v73
	global_store_dwordx2 v[52:53], v[38:39], off offset:64
	v_pk_add_f32 v[34:35], v[84:85], v[34:35]
	v_pk_add_f32 v[36:37], v[36:37], v[74:75]
	v_mov_b32_e32 v38, v80
	v_mov_b32_e32 v39, v76
	v_pk_add_f32 v[40:41], v[68:69], v[40:41]
	v_pk_add_f32 v[36:37], v[38:39], v[36:37]
	v_mov_b32_e32 v76, v81
	v_pk_add_f32 v[36:37], v[76:77], v[36:37]
	v_or_b32_e32 v38, 32, v90
	v_ashrrev_i32_e32 v39, 31, v38
	v_lshlrev_b64 v[38:39], 11, v[38:39]
	v_pk_mul_f32 v[46:47], v[46:47], v[50:51] op_sel_hi:[1,0]
	v_pk_mul_f32 v[48:49], v[48:49], v[50:51] op_sel_hi:[1,0]
	v_cvt_pk_bf16_f32 v46, v46, v47
	s_waitcnt vmcnt(8)
	v_mov_b32_e32 v42, v98
	s_waitcnt vmcnt(7)
	v_mov_b32_e32 v43, v102
	v_mov_b32_e32 v102, v99
	v_pk_add_f32 v[42:43], v[42:43], v[102:103]
	v_mov_b32_e32 v44, v100
	v_mov_b32_e32 v45, v104
	v_pk_add_f32 v[42:43], v[44:45], v[42:43]
	v_mov_b32_e32 v104, v101
	v_mov_b32_e32 v44, v40
	v_mov_b32_e32 v45, v34
	v_pk_add_f32 v[42:43], v[104:105], v[42:43]
	v_pk_add_f32 v[44:45], v[44:45], 0 op_sel_hi:[1,0]
	v_mov_b32_e32 v34, v41
	v_pk_add_f32 v[34:35], v[44:45], v[34:35]
	v_mov_b32_e32 v40, v42
	v_mov_b32_e32 v41, v36
	v_pk_add_f32 v[34:35], v[34:35], v[40:41]
	v_mov_b32_e32 v36, v43
	v_pk_add_f32 v[34:35], v[34:35], v[36:37]
	v_cvt_pk_bf16_f32 v47, v48, v49
	global_store_dwordx2 v[52:53], v[46:47], off
	v_pk_fma_f32 v[34:35], v[34:35], s[2:3], v[92:93] op_sel_hi:[1,0,0]
	s_add_i32 s2, s1, s42
	v_mul_f32_e32 v36, 0x4b800000, v35
	v_cmp_gt_f32_e32 vcc, s6, v35
	s_cmpk_lt_u32 s2, 0x80
	s_nop 0
	v_cndmask_b32_e32 v35, v35, v36, vcc
	v_rsq_f32_e32 v35, v35
	v_lshl_add_u64 v[36:37], s[14:15], 0, v[38:39]
	v_lshl_add_u64 v[36:37], v[36:37], 0, v[0:1]
	v_or_b32_e32 v38, 48, v90
	v_mul_f32_e32 v39, 0x45800000, v35
	v_cndmask_b32_e32 v40, v35, v39, vcc
	v_pk_mul_f32 v[22:23], v[22:23], v[40:41] op_sel_hi:[1,0]
	v_pk_mul_f32 v[24:25], v[24:25], v[40:41] op_sel_hi:[1,0]
	v_cvt_pk_bf16_f32 v22, v22, v23
	v_cmp_gt_f32_e32 vcc, s6, v34
	v_cvt_pk_bf16_f32 v23, v24, v25
	global_store_dwordx2 v[36:37], v[22:23], off offset:64
	v_mul_f32_e32 v22, 0x4b800000, v34
	v_cndmask_b32_e32 v22, v34, v22, vcc
	v_rsq_f32_e32 v22, v22
	v_pk_mul_f32 v[18:19], v[18:19], v[40:41] op_sel_hi:[1,0]
	v_pk_mul_f32 v[20:21], v[20:21], v[40:41] op_sel_hi:[1,0]
	v_cvt_pk_bf16_f32 v18, v18, v19
	v_ashrrev_i32_e32 v39, 31, v38
	v_cvt_pk_bf16_f32 v19, v20, v21
	global_store_dwordx2 v[36:37], v[18:19], off offset:96
	v_mul_f32_e32 v18, 0x45800000, v22
	v_cndmask_b32_e32 v18, v22, v18, vcc
	v_lshlrev_b64 v[20:21], 11, v[38:39]
	v_lshl_add_u64 v[20:21], s[14:15], 0, v[20:21]
	v_pk_mul_f32 v[4:5], v[4:5], v[18:19] op_sel_hi:[1,0]
	v_pk_mul_f32 v[2:3], v[2:3], v[18:19] op_sel_hi:[1,0]
	v_pk_mul_f32 v[30:31], v[30:31], v[40:41] op_sel_hi:[1,0]
	v_pk_mul_f32 v[26:27], v[26:27], v[40:41] op_sel_hi:[1,0]
	v_lshl_add_u64 v[20:21], v[20:21], 0, v[0:1]
	v_pk_mul_f32 v[14:15], v[14:15], v[18:19] op_sel_hi:[1,0]
	v_pk_mul_f32 v[6:7], v[6:7], v[18:19] op_sel_hi:[1,0]
	v_cvt_pk_bf16_f32 v2, v2, v3
	v_cvt_pk_bf16_f32 v3, v4, v5
	v_pk_mul_f32 v[4:5], v[10:11], v[18:19] op_sel_hi:[1,0]
	v_pk_mul_f32 v[32:33], v[32:33], v[40:41] op_sel_hi:[1,0]
	v_cvt_pk_bf16_f32 v30, v30, v31
	v_pk_mul_f32 v[28:29], v[28:29], v[40:41] op_sel_hi:[1,0]
	v_cvt_pk_bf16_f32 v31, v32, v33
	global_store_dwordx2 v[36:37], v[30:31], off
	v_cvt_pk_bf16_f32 v26, v26, v27
	v_cvt_pk_bf16_f32 v27, v28, v29
	global_store_dwordx2 v[36:37], v[26:27], off offset:32
	v_pk_mul_f32 v[16:17], v[16:17], v[18:19] op_sel_hi:[1,0]
	v_cvt_pk_bf16_f32 v14, v14, v15
	v_pk_mul_f32 v[8:9], v[8:9], v[18:19] op_sel_hi:[1,0]
	v_cvt_pk_bf16_f32 v15, v16, v17
	global_store_dwordx2 v[20:21], v[14:15], off
	v_cvt_pk_bf16_f32 v6, v6, v7
	v_cvt_pk_bf16_f32 v7, v8, v9
	global_store_dwordx2 v[20:21], v[6:7], off offset:32
	global_store_dwordx2 v[20:21], v[2:3], off offset:64
	v_pk_mul_f32 v[2:3], v[12:13], v[18:19] op_sel_hi:[1,0]
	v_cvt_pk_bf16_f32 v4, v4, v5
	s_nop 0
	v_cvt_pk_bf16_f32 v5, v2, v3
	global_store_dwordx2 v[20:21], v[4:5], off offset:96
	s_cbranch_scc1 .LBB0_975
	s_mov_b32 s45, 0x800000
